# one static s_setprio 1 for waves 4-7 at kernel entry, no per-segment priority toggles in the GEMM loops
# speedup vs baseline: 1.0033x; 1.0033x over previous
; #define LAS __attribute__((address_space(3)))
; __device__ __forceinline__ void p0_transpose_item(const float* W, int K, int N, bf16r* WT, LAS float* scr, int item, int lane) {
;     const int nblk = N / 64, kb = item / nblk, nb = item % nblk, k0 = 64 * kb, n0 = 64 * nb;
; #pragma unroll 8
;     for (int i = 0; i < 32; ++i) { const int kk = 2 * i + (lane >> 5); const f32x2 v = *(const f32x2*)(W + (size_t)(k0 + kk) * N + n0 + 2 * (lane & 31)); scr[kk * 65 + 2 * (lane & 31)] = v.x; scr[kk * 65 + 2 * (lane & 31) + 1] = v.y; }
; __device__ __forceinline__ void prologue(const Args& a, unsigned char* lds, int vcu, int G, int wave, int lane) {
;     LAS float* scr = (LAS float*)((LAS unsigned char*)lds + wave * 16640);
;     const int gw = vcu * NWAVES + wave, NGW = G * NWAVES;
;     constexpr int I_IN = (DM / 64) * (DIN / 64), I_OUT = (DM / 64) * (DM / 64), NITEMS = 2 * (I_IN + I_OUT);
;     bf16r* WinT = (bf16r*)(a.ws + WS_WINT); bf16r* WoutT = (bf16r*)(a.ws + WS_WOUTT);
;     for (int it = gw; it < NITEMS; it += NGW) {
;         int r = it;
;         if (r < I_IN) { p0_transpose_item(a.in[3], DM, DIN, WinT, scr, r, lane); continue; } r -= I_IN;
.LBB0_12:
	s_lshr_b32 s55, s50, 6
	s_cmp_lt_u32 s55, 4
	s_cbranch_scc1 .Lsp_skip
	s_setprio 1
.Lsp_skip:
	s_cmp_gt_i32 s5, 0
	s_cselect_b64 s[2:3], -1, 0
	s_and_b64 s[2:3], s[6:7], s[2:3]
	s_andn2_b64 vcc, exec, s[2:3]
	v_and_b32_e32 v193, 63, v192
	s_cbranch_vccnz .LBB0_59
	s_load_dwordx8 s[12:19], s[0:1], 0x0
	s_load_dwordx2 s[24:25], s[0:1], 0x80
	s_lshl_b32 s2, s33, 3
	s_add_i32 s26, s2, s55
	s_lshl_b32 s36, s28, 3
	s_lshl_b32 s23, s26, 6
	s_lshl_b32 s22, s28, 9
	s_cmp_gt_i32 s26, 0x8fff
	s_cbranch_scc1 .LBB0_36
	v_lshlrev_b32_e32 v2, 3, v192
	v_and_b32_e32 v2, 56, v2
	s_mul_i32 s2, s55, 0x4100
	v_lshrrev_b32_e32 v36, 3, v193
	v_mul_u32_u24_e32 v8, 0x104, v2
	v_lshlrev_b32_e32 v2, 1, v2
	v_mov_b32_e32 v3, 0
	s_add_i32 s6, s2, 0
	v_lshl_add_u64 v[4:5], s[30:31], 0, v[2:3]
	v_lshlrev_b32_e32 v2, 2, v36
	v_add3_u32 v37, s6, v8, v2
	s_load_dwordx2 s[6:7], s[0:1], 0x68
	v_lshrrev_b32_e32 v1, 5, v193
	s_movk_i32 s27, 0x104
	v_mov_b32_e32 v2, s2
	s_mov_b64 s[4:5], 0x10000000
	v_mad_u32_u24 v12, v1, s27, v2
	v_and_b32_e32 v2, 31, v192
	v_lshl_add_u64 v[6:7], v[4:5], 0, s[4:5]
	s_mov_b64 s[4:5], 0x7000000
	v_lshlrev_b32_e32 v2, 3, v2
	v_lshl_add_u64 v[8:9], v[4:5], 0, s[4:5]
	s_mov_b64 s[4:5], 0xe000000
	v_add3_u32 v45, v12, v2, 0
	s_waitcnt lgkmcnt(0)
	v_lshl_add_u64 v[12:13], s[6:7], 0, v[2:3]
	s_mov_b64 s[6:7], 0x4000000
	v_lshl_add_u64 v[16:17], s[18:19], 0, v[2:3]
	s_mov_b32 s3, 0
	v_or_b32_e32 v38, 8, v36
	v_or_b32_e32 v39, 16, v36
	v_or_b32_e32 v40, 24, v36
	v_or_b32_e32 v41, 32, v36
	v_or_b32_e32 v42, 40, v36
	v_or_b32_e32 v43, 48, v36
	v_or_b32_e32 v44, 56, v36
	v_lshl_add_u64 v[10:11], v[4:5], 0, s[4:5]
	v_lshl_add_u64 v[14:15], v[12:13], 0, s[6:7]
	v_or_b32_e32 v46, 14, v1
	v_or_b32_e32 v47, 12, v1
	v_or_b32_e32 v48, 10, v1
	v_or_b32_e32 v49, 8, v1
	v_or_b32_e32 v50, 6, v1
	v_or_b32_e32 v51, 4, v1
	v_or_b32_e32 v52, 2, v1
	v_lshl_add_u64 v[18:19], v[16:17], 0, s[4:5]
	s_add_i32 s27, s26, 0xc800
	s_mov_b32 s37, 0xe000
	v_mov_b32_e32 v53, 0x8000
	v_add_u32_e32 v54, 0x400, v37
	s_mov_b32 s38, s23
	s_mov_b32 s39, s26
	s_branch .LBB0_16

; #define PG8_STAGE(bufoff, gbase, voff) do { _Pragma("unroll") for (int _i = 0; _i < 2; ++_i) \
;         __builtin_amdgcn_global_load_lds((const unsigned*)((const char*)(gbase) + (voff)[_i]), (PG8_LAS unsigned*)(lds + (bufoff) + ldsw + _i * 8192), 16, 0, 0); } while (0)
; #define PG8_LDA(dst, b, h) do { _Pragma("unroll") for (int m = 0; m < 4; ++m) _Pragma("unroll") for (int k = 0; k < 2; ++k) dst[m][k] = *(const PG8_LAS bf16x8*)(lds + PG8_SA(b, h) + aoff + m * 2048 + k * 1024); } while (0)
; #define PG8_LDB(dst, b, h) do { _Pragma("unroll") for (int n = 0; n < 2; ++n) _Pragma("unroll") for (int k = 0; k < 2; ++k) dst[n][k] = *(const PG8_LAS bf16x8*)(lds + PG8_SB(b, h) + boff + n * 2048 + k * 1024); } while (0)
; #define PG8_MMA(ai, bj, At, Bt) do { __builtin_amdgcn_s_setprio(1); _Pragma("unroll") for (int m = 0; m < 4; ++m) _Pragma("unroll") for (int n = 0; n < 2; ++n) _Pragma("unroll") for (int k = 0; k < 2; ++k) \
;         acc[ai][bj][m][n] = __builtin_amdgcn_mfma_f32_16x16x32_bf16(Bt[n][k], At[m][k], acc[ai][bj][m][n], 0, 0, 0); __builtin_amdgcn_s_setprio(0); } while (0)
; #define PG8_WAIT_V(n) asm volatile("s_waitcnt vmcnt(" #n ")" ::: "memory")
; #define PG8_WAIT_L(n) asm volatile("s_waitcnt lgkmcnt(" #n ")" ::: "memory")
; #define PG8_BAR __builtin_amdgcn_s_barrier()
; #define PG8_SCHED __builtin_amdgcn_sched_barrier(0)
; template <class Epi, class Sched, bool ALIGN_EPI = false, bool SP2 = false>
; __device__ __forceinline__ void gemm_phase(PG8_LAS unsigned char* lds, const Gemm g, const Sched& S, const Epi& E) {
;     ...
;             PG8_LDB(B0, 0, 0); PG8_LDB(B1, 0, 1); PG8_SCHED; PG8_LDA(At, 0, 0); PG8_STAGE(PG8_SA(1, 1), a1 + hstep, voffA);
;             PG8_WAIT_V(8); PG8_WAIT_L(0); PG8_BAR; PG8_MMA(0, 0, At, B0); PG8_MMA(0, 1, At, B1); PG8_BAR; PG8_SCHED;
;             PG8_LDA(At, 0, 1); PG8_STAGE(PG8_SB(0, 0), b2, voffB); PG8_STAGE(PG8_SB(0, 1), b2 + hstep, voffB); PG8_STAGE(PG8_SA(0, 0), a2, voffA);
;             PG8_WAIT_V(8); PG8_WAIT_L(0); PG8_BAR; PG8_MMA(1, 0, At, B0); PG8_MMA(1, 1, At, B1); PG8_BAR; PG8_SCHED;
.LBB0_86:
	ds_read_b128 v[128:131], v188
	ds_read_b128 v[132:135], v188 offset:1024
	ds_read_b128 v[136:139], v188 offset:2048
	ds_read_b128 v[140:143], v188 offset:3072
	ds_read_b128 v[168:171], v189
	ds_read_b128 v[172:175], v189 offset:1024
	ds_read_b128 v[176:179], v189 offset:2048
	ds_read_b128 v[180:183], v189 offset:3072
	s_add_u32 s72, s8, 0xfff00080
	s_addc_u32 s73, s9, -1
	s_cmp_eq_u32 s91, 60
	s_cselect_b32 s75, s7, s73
	s_cselect_b32 s74, s13, s72
	s_cselect_b32 s73, s16, s90
	s_cselect_b32 s72, s65, s67
	v_lshl_add_u64 v[184:185], s[8:9], 0, v[160:161]
	s_add_i32 m0, s63, 0xc000
	ds_read_b128 v[196:199], v190
	ds_read_b128 v[200:203], v190 offset:1024
	ds_read_b128 v[204:207], v190 offset:2048
	ds_read_b128 v[208:211], v190 offset:3072
	ds_read_b128 v[212:215], v190 offset:4096
	ds_read_b128 v[216:219], v190 offset:5120
	ds_read_b128 v[220:223], v190 offset:6144
	ds_read_b128 v[224:227], v190 offset:7168
	global_load_lds_dwordx4 v[184:185], off
	v_lshl_add_u64 v[184:185], s[8:9], 0, v[162:163]
	s_add_i32 m0, s63, 0xe000
	s_nop 0
	global_load_lds_dwordx4 v[184:185], off
	s_waitcnt vmcnt(8)
	s_waitcnt lgkmcnt(0)
	s_barrier
	s_waitcnt lgkmcnt(0)
	v_mfma_f32_16x16x32_bf16 v[124:127], v[128:131], v[196:199], v[124:127]
	v_mfma_f32_16x16x32_bf16 v[120:123], v[136:139], v[196:199], v[120:123]
	v_mfma_f32_16x16x32_bf16 v[108:111], v[128:131], v[204:207], v[108:111]
	v_mfma_f32_16x16x32_bf16 v[104:107], v[136:139], v[204:207], v[104:107]
	v_mfma_f32_16x16x32_bf16 v[92:95], v[128:131], v[212:215], v[92:95]
	v_mfma_f32_16x16x32_bf16 v[88:91], v[136:139], v[212:215], v[88:91]
	v_mfma_f32_16x16x32_bf16 v[76:79], v[128:131], v[220:223], v[76:79]
	v_mfma_f32_16x16x32_bf16 v[72:75], v[136:139], v[220:223], v[72:75]
	v_mfma_f32_16x16x32_bf16 v[124:127], v[132:135], v[200:203], v[124:127]
	v_mfma_f32_16x16x32_bf16 v[120:123], v[140:143], v[200:203], v[120:123]
	v_mfma_f32_16x16x32_bf16 v[108:111], v[132:135], v[208:211], v[108:111]
	v_mfma_f32_16x16x32_bf16 v[104:107], v[140:143], v[208:211], v[104:107]
	v_mfma_f32_16x16x32_bf16 v[92:95], v[132:135], v[216:219], v[92:95]
	v_mfma_f32_16x16x32_bf16 v[88:91], v[140:143], v[216:219], v[88:91]
	v_mfma_f32_16x16x32_bf16 v[76:79], v[132:135], v[224:227], v[76:79]
	v_mfma_f32_16x16x32_bf16 v[72:75], v[140:143], v[224:227], v[72:75]
	v_mfma_f32_16x16x32_bf16 v[116:119], v[168:171], v[196:199], v[116:119]
	v_mfma_f32_16x16x32_bf16 v[112:115], v[176:179], v[196:199], v[112:115]
	v_mfma_f32_16x16x32_bf16 v[100:103], v[168:171], v[204:207], v[100:103]
	v_mfma_f32_16x16x32_bf16 v[96:99], v[176:179], v[204:207], v[96:99]
	v_mfma_f32_16x16x32_bf16 v[84:87], v[168:171], v[212:215], v[84:87]
	v_mfma_f32_16x16x32_bf16 v[80:83], v[176:179], v[212:215], v[80:83]
	v_mfma_f32_16x16x32_bf16 v[68:71], v[168:171], v[220:223], v[68:71]
	v_mfma_f32_16x16x32_bf16 v[64:67], v[176:179], v[220:223], v[64:67]
	v_mfma_f32_16x16x32_bf16 v[116:119], v[172:175], v[200:203], v[116:119]
	v_mfma_f32_16x16x32_bf16 v[112:115], v[180:183], v[200:203], v[112:115]
	v_mfma_f32_16x16x32_bf16 v[100:103], v[172:175], v[208:211], v[100:103]
	v_mfma_f32_16x16x32_bf16 v[96:99], v[180:183], v[208:211], v[96:99]
	v_mfma_f32_16x16x32_bf16 v[84:87], v[172:175], v[216:219], v[84:87]
	v_mfma_f32_16x16x32_bf16 v[80:83], v[180:183], v[216:219], v[80:83]
	v_mfma_f32_16x16x32_bf16 v[68:71], v[172:175], v[224:227], v[68:71]
	v_mfma_f32_16x16x32_bf16 v[64:67], v[180:183], v[224:227], v[64:67]
	s_barrier
	s_add_i32 s92, s87, s61
	v_lshl_add_u64 v[184:185], s[72:73], 0, v[146:147]
	s_mov_b32 m0, s92
	ds_read_b128 v[196:199], v190 offset:16384
	ds_read_b128 v[200:203], v190 offset:17408
	ds_read_b128 v[204:207], v190 offset:18432
	ds_read_b128 v[208:211], v190 offset:19456
	ds_read_b128 v[212:215], v190 offset:20480
	ds_read_b128 v[216:219], v190 offset:21504
	ds_read_b128 v[220:223], v190 offset:22528
	ds_read_b128 v[224:227], v190 offset:23552
	global_load_lds_dwordx4 v[184:185], off
	s_add_i32 m0, s92, 0x2000
	s_add_u32 s92, s72, 0x100000
	v_lshl_add_u64 v[228:229], s[72:73], 0, v[150:151]
	s_addc_u32 s93, s73, 0
	s_add_i32 s94, s88, s61
	global_load_lds_dwordx4 v[228:229], off
	v_lshl_add_u64 v[230:231], s[92:93], 0, v[146:147]
	s_mov_b32 m0, s94
	v_lshl_add_u64 v[232:233], s[74:75], 0, v[148:149]
	global_load_lds_dwordx4 v[230:231], off
	v_lshl_add_u64 v[230:231], s[92:93], 0, v[150:151]
	s_add_i32 m0, s94, 0x2000
	s_nop 0
	global_load_lds_dwordx4 v[230:231], off
	v_lshl_add_u64 v[230:231], s[74:75], 0, v[144:145]
	s_mov_b32 m0, s63
	s_nop 0
	global_load_lds_dwordx4 v[230:231], off
	s_mov_b32 m0, s76
	s_nop 0
	global_load_lds_dwordx4 v[232:233], off
	s_waitcnt vmcnt(8)
	s_waitcnt lgkmcnt(0)
	s_barrier
; #define PG8_STAGE(bufoff, gbase, voff) do { _Pragma("unroll") for (int _i = 0; _i < 2; ++_i) \
;         __builtin_amdgcn_global_load_lds((const unsigned*)((const char*)(gbase) + (voff)[_i]), (PG8_LAS unsigned*)(lds + (bufoff) + ldsw + _i * 8192), 16, 0, 0); } while (0)
; #define PG8_LDA(dst, b, h) do { _Pragma("unroll") for (int m = 0; m < 4; ++m) _Pragma("unroll") for (int k = 0; k < 2; ++k) dst[m][k] = *(const PG8_LAS bf16x8*)(lds + PG8_SA(b, h) + aoff + m * 2048 + k * 1024); } while (0)
; #define PG8_LDB(dst, b, h) do { _Pragma("unroll") for (int n = 0; n < 2; ++n) _Pragma("unroll") for (int k = 0; k < 2; ++k) dst[n][k] = *(const PG8_LAS bf16x8*)(lds + PG8_SB(b, h) + boff + n * 2048 + k * 1024); } while (0)
; #define PG8_MMA(ai, bj, At, Bt) do { __builtin_amdgcn_s_setprio(1); _Pragma("unroll") for (int m = 0; m < 4; ++m) _Pragma("unroll") for (int n = 0; n < 2; ++n) _Pragma("unroll") for (int k = 0; k < 2; ++k) \
;         acc[ai][bj][m][n] = __builtin_amdgcn_mfma_f32_16x16x32_bf16(Bt[n][k], At[m][k], acc[ai][bj][m][n], 0, 0, 0); __builtin_amdgcn_s_setprio(0); } while (0)
; #define PG8_WAIT_V(n) asm volatile("s_waitcnt vmcnt(" #n ")" ::: "memory")
; #define PG8_WAIT_L(n) asm volatile("s_waitcnt lgkmcnt(" #n ")" ::: "memory")
; #define PG8_BAR __builtin_amdgcn_s_barrier()
; #define PG8_SCHED __builtin_amdgcn_sched_barrier(0)
; template <class Epi, class Sched, bool ALIGN_EPI = false, bool SP2 = false>
; __device__ __forceinline__ void gemm_phase(PG8_LAS unsigned char* lds, const Gemm g, const Sched& S, const Epi& E) {
;     ...
;             PG8_WAIT_V(8); PG8_WAIT_L(0); PG8_BAR; PG8_MMA(1, 0, At, B0); PG8_MMA(1, 1, At, B1); PG8_BAR; PG8_SCHED;
;             PG8_LDB(B0, 1, 0); PG8_LDB(B1, 1, 1); PG8_SCHED; PG8_LDA(At, 1, 0); PG8_STAGE(PG8_SA(0, 1), a2 + hstep, voffA);
;             PG8_WAIT_V(8); PG8_WAIT_L(0); PG8_BAR; PG8_MMA(0, 0, At, B0); PG8_MMA(0, 1, At, B1); PG8_BAR; PG8_SCHED;
	s_waitcnt lgkmcnt(0)
	v_mfma_f32_16x16x32_bf16 v[60:63], v[128:131], v[196:199], v[60:63]
	v_mfma_f32_16x16x32_bf16 v[56:59], v[136:139], v[196:199], v[56:59]
	v_mfma_f32_16x16x32_bf16 v[44:47], v[128:131], v[204:207], v[44:47]
	v_mfma_f32_16x16x32_bf16 v[40:43], v[136:139], v[204:207], v[40:43]
	v_mfma_f32_16x16x32_bf16 v[28:31], v[128:131], v[212:215], v[28:31]
	v_mfma_f32_16x16x32_bf16 v[24:27], v[136:139], v[212:215], v[24:27]
	v_mfma_f32_16x16x32_bf16 v[12:15], v[128:131], v[220:223], v[12:15]
	v_mfma_f32_16x16x32_bf16 v[8:11], v[136:139], v[220:223], v[8:11]
	v_mfma_f32_16x16x32_bf16 v[60:63], v[132:135], v[200:203], v[60:63]
	v_mfma_f32_16x16x32_bf16 v[56:59], v[140:143], v[200:203], v[56:59]
	v_mfma_f32_16x16x32_bf16 v[44:47], v[132:135], v[208:211], v[44:47]
	v_mfma_f32_16x16x32_bf16 v[40:43], v[140:143], v[208:211], v[40:43]
	v_mfma_f32_16x16x32_bf16 v[28:31], v[132:135], v[216:219], v[28:31]
	v_mfma_f32_16x16x32_bf16 v[24:27], v[140:143], v[216:219], v[24:27]
	v_mfma_f32_16x16x32_bf16 v[12:15], v[132:135], v[224:227], v[12:15]
	v_mfma_f32_16x16x32_bf16 v[8:11], v[140:143], v[224:227], v[8:11]
	v_mfma_f32_16x16x32_bf16 v[52:55], v[168:171], v[196:199], v[52:55]
	v_mfma_f32_16x16x32_bf16 v[48:51], v[176:179], v[196:199], v[48:51]
	v_mfma_f32_16x16x32_bf16 v[36:39], v[168:171], v[204:207], v[36:39]
	v_mfma_f32_16x16x32_bf16 v[32:35], v[176:179], v[204:207], v[32:35]
	v_mfma_f32_16x16x32_bf16 v[20:23], v[168:171], v[212:215], v[20:23]
	v_mfma_f32_16x16x32_bf16 v[16:19], v[176:179], v[212:215], v[16:19]
	v_mfma_f32_16x16x32_bf16 v[4:7], v[168:171], v[220:223], v[4:7]
	v_mfma_f32_16x16x32_bf16 v[0:3], v[176:179], v[220:223], v[0:3]
	v_mfma_f32_16x16x32_bf16 v[52:55], v[172:175], v[200:203], v[52:55]
	v_mfma_f32_16x16x32_bf16 v[48:51], v[180:183], v[200:203], v[48:51]
	v_mfma_f32_16x16x32_bf16 v[36:39], v[172:175], v[208:211], v[36:39]
	v_mfma_f32_16x16x32_bf16 v[32:35], v[180:183], v[208:211], v[32:35]
	v_mfma_f32_16x16x32_bf16 v[20:23], v[172:175], v[216:219], v[20:23]
	v_mfma_f32_16x16x32_bf16 v[16:19], v[180:183], v[216:219], v[16:19]
	v_mfma_f32_16x16x32_bf16 v[4:7], v[172:175], v[224:227], v[4:7]
	v_mfma_f32_16x16x32_bf16 v[0:3], v[180:183], v[224:227], v[0:3]
	s_barrier
	s_add_i32 s92, 0, 0x18000
	s_add_i32 s93, 0, 0x1c000
	v_add_u32_e32 v140, s92, v187
	v_add_u32_e32 v152, s93, v187
	ds_read_b128 v[128:131], v140
	ds_read_b128 v[132:135], v140 offset:1024
	ds_read_b128 v[136:139], v140 offset:2048
	ds_read_b128 v[140:143], v140 offset:3072
	ds_read_b128 v[168:171], v152
	ds_read_b128 v[172:175], v152 offset:1024
	ds_read_b128 v[176:179], v152 offset:2048
	ds_read_b128 v[180:183], v152 offset:3072
	s_add_u32 s74, s74, 0x100000
	s_addc_u32 s75, s75, 0
	s_mov_b32 m0, s77
	v_lshl_add_u64 v[234:235], s[74:75], 0, v[144:145]
	ds_read_b128 v[196:199], v190 offset:32768
	ds_read_b128 v[200:203], v190 offset:33792
	ds_read_b128 v[204:207], v190 offset:34816
	ds_read_b128 v[208:211], v190 offset:35840
	ds_read_b128 v[212:215], v190 offset:36864
	ds_read_b128 v[216:219], v190 offset:37888
	ds_read_b128 v[220:223], v190 offset:38912
	ds_read_b128 v[224:227], v190 offset:39936
	global_load_lds_dwordx4 v[234:235], off
	v_lshl_add_u64 v[234:235], s[74:75], 0, v[148:149]
	s_mov_b32 m0, s78
	s_nop 0
	global_load_lds_dwordx4 v[234:235], off
	s_waitcnt vmcnt(8)
	s_waitcnt lgkmcnt(0)
	s_barrier
	s_waitcnt lgkmcnt(0)
	v_mfma_f32_16x16x32_bf16 v[124:127], v[128:131], v[196:199], v[124:127]
	v_mfma_f32_16x16x32_bf16 v[120:123], v[136:139], v[196:199], v[120:123]
	v_mfma_f32_16x16x32_bf16 v[108:111], v[128:131], v[204:207], v[108:111]
	v_mfma_f32_16x16x32_bf16 v[104:107], v[136:139], v[204:207], v[104:107]
	v_mfma_f32_16x16x32_bf16 v[92:95], v[128:131], v[212:215], v[92:95]
	v_mfma_f32_16x16x32_bf16 v[88:91], v[136:139], v[212:215], v[88:91]
	v_mfma_f32_16x16x32_bf16 v[76:79], v[128:131], v[220:223], v[76:79]
	v_mfma_f32_16x16x32_bf16 v[72:75], v[136:139], v[220:223], v[72:75]
	v_mfma_f32_16x16x32_bf16 v[124:127], v[132:135], v[200:203], v[124:127]
	v_mfma_f32_16x16x32_bf16 v[120:123], v[140:143], v[200:203], v[120:123]
	v_mfma_f32_16x16x32_bf16 v[108:111], v[132:135], v[208:211], v[108:111]
	v_mfma_f32_16x16x32_bf16 v[104:107], v[140:143], v[208:211], v[104:107]
	v_mfma_f32_16x16x32_bf16 v[92:95], v[132:135], v[216:219], v[92:95]
	v_mfma_f32_16x16x32_bf16 v[88:91], v[140:143], v[216:219], v[88:91]
	v_mfma_f32_16x16x32_bf16 v[76:79], v[132:135], v[224:227], v[76:79]
	v_mfma_f32_16x16x32_bf16 v[72:75], v[140:143], v[224:227], v[72:75]
	v_mfma_f32_16x16x32_bf16 v[116:119], v[168:171], v[196:199], v[116:119]
	v_mfma_f32_16x16x32_bf16 v[112:115], v[176:179], v[196:199], v[112:115]
	v_mfma_f32_16x16x32_bf16 v[100:103], v[168:171], v[204:207], v[100:103]
	v_mfma_f32_16x16x32_bf16 v[96:99], v[176:179], v[204:207], v[96:99]
	v_mfma_f32_16x16x32_bf16 v[84:87], v[168:171], v[212:215], v[84:87]
	v_mfma_f32_16x16x32_bf16 v[80:83], v[176:179], v[212:215], v[80:83]
	v_mfma_f32_16x16x32_bf16 v[68:71], v[168:171], v[220:223], v[68:71]
	v_mfma_f32_16x16x32_bf16 v[64:67], v[176:179], v[220:223], v[64:67]
	v_mfma_f32_16x16x32_bf16 v[116:119], v[172:175], v[200:203], v[116:119]
	v_mfma_f32_16x16x32_bf16 v[112:115], v[180:183], v[200:203], v[112:115]
	v_mfma_f32_16x16x32_bf16 v[100:103], v[172:175], v[208:211], v[100:103]
	v_mfma_f32_16x16x32_bf16 v[96:99], v[180:183], v[208:211], v[96:99]
	v_mfma_f32_16x16x32_bf16 v[84:87], v[172:175], v[216:219], v[84:87]
	v_mfma_f32_16x16x32_bf16 v[80:83], v[180:183], v[216:219], v[80:83]
	v_mfma_f32_16x16x32_bf16 v[68:71], v[172:175], v[224:227], v[68:71]
	v_mfma_f32_16x16x32_bf16 v[64:67], v[180:183], v[224:227], v[64:67]
	s_barrier
; #define PG8_STAGE(bufoff, gbase, voff) do { _Pragma("unroll") for (int _i = 0; _i < 2; ++_i) \
;         __builtin_amdgcn_global_load_lds((const unsigned*)((const char*)(gbase) + (voff)[_i]), (PG8_LAS unsigned*)(lds + (bufoff) + ldsw + _i * 8192), 16, 0, 0); } while (0)
; #define PG8_LDA(dst, b, h) do { _Pragma("unroll") for (int m = 0; m < 4; ++m) _Pragma("unroll") for (int k = 0; k < 2; ++k) dst[m][k] = *(const PG8_LAS bf16x8*)(lds + PG8_SA(b, h) + aoff + m * 2048 + k * 1024); } while (0)
; #define PG8_MMA(ai, bj, At, Bt) do { __builtin_amdgcn_s_setprio(1); _Pragma("unroll") for (int m = 0; m < 4; ++m) _Pragma("unroll") for (int n = 0; n < 2; ++n) _Pragma("unroll") for (int k = 0; k < 2; ++k) \
;         acc[ai][bj][m][n] = __builtin_amdgcn_mfma_f32_16x16x32_bf16(Bt[n][k], At[m][k], acc[ai][bj][m][n], 0, 0, 0); __builtin_amdgcn_s_setprio(0); } while (0)
; #define PG8_WAIT_V(n) asm volatile("s_waitcnt vmcnt(" #n ")" ::: "memory")
; #define PG8_WAIT_L(n) asm volatile("s_waitcnt lgkmcnt(" #n ")" ::: "memory")
; #define PG8_BAR __builtin_amdgcn_s_barrier()
; #define PG8_SCHED __builtin_amdgcn_sched_barrier(0)
; template <class Epi, class Sched, bool ALIGN_EPI = false, bool SP2 = false>
; __device__ __forceinline__ void gemm_phase(PG8_LAS unsigned char* lds, const Gemm g, const Sched& S, const Epi& E) {
;     ...
;         for (int t = 0; t < nt; t += 2) {
;             const bool last = (t == nt - 2);
;             const char* a1 = cA + (size_t)(t + 1) * kstep;
;             const char* a2 = last ? nA : cA + (size_t)(t + 2) * kstep; const char* b2 = last ? nB : cB + (size_t)(t + 2) * kstep;
;     ...
;             PG8_LDA(At, 1, 1); PG8_STAGE(PG8_SB(1, 0), b3, voffB); PG8_STAGE(PG8_SB(1, 1), b3 + hstep, voffB); PG8_STAGE(PG8_SA(1, 0), a3, voffA);
;             PG8_WAIT_V(8); PG8_WAIT_L(0); PG8_BAR; PG8_MMA(1, 0, At, B0); PG8_MMA(1, 1, At, B1); PG8_BAR; PG8_SCHED;
	s_add_i32 s74, s92, s61
	v_lshl_add_u64 v[184:185], v[184:185], 0, s[22:23]
	s_mov_b32 m0, s74
	ds_read_b128 v[196:199], v190 offset:49152
	ds_read_b128 v[200:203], v190 offset:50176
	ds_read_b128 v[204:207], v190 offset:51200
	ds_read_b128 v[208:211], v190 offset:52224
	ds_read_b128 v[212:215], v190 offset:53248
	ds_read_b128 v[216:219], v190 offset:54272
	ds_read_b128 v[220:223], v190 offset:55296
	ds_read_b128 v[224:227], v190 offset:56320
	global_load_lds_dwordx4 v[184:185], off
	s_add_i32 m0, s74, 0x2000
	s_add_u32 s72, s72, 0x100080
	v_lshl_add_u64 v[184:185], v[228:229], 0, s[22:23]
	s_addc_u32 s73, s73, 0
	s_add_i32 s74, s93, s61
	global_load_lds_dwordx4 v[184:185], off
	v_lshl_add_u64 v[184:185], s[72:73], 0, v[146:147]
	s_mov_b32 m0, s74
	s_nop 0
	global_load_lds_dwordx4 v[184:185], off
	v_lshl_add_u64 v[184:185], s[72:73], 0, v[150:151]
	s_add_i32 m0, s74, 0x2000
	s_nop 0
	global_load_lds_dwordx4 v[184:185], off
	v_lshl_add_u64 v[184:185], v[230:231], 0, s[22:23]
	s_mov_b32 m0, s83
	s_nop 0
	global_load_lds_dwordx4 v[184:185], off
	v_lshl_add_u64 v[184:185], v[232:233], 0, s[22:23]
	s_mov_b32 m0, s84
	s_nop 0
	global_load_lds_dwordx4 v[184:185], off
	s_waitcnt vmcnt(8)
	s_waitcnt lgkmcnt(0)
	s_barrier
	s_waitcnt lgkmcnt(0)
	v_mfma_f32_16x16x32_bf16 v[60:63], v[128:131], v[196:199], v[60:63]
	v_mfma_f32_16x16x32_bf16 v[56:59], v[136:139], v[196:199], v[56:59]
	v_mfma_f32_16x16x32_bf16 v[44:47], v[128:131], v[204:207], v[44:47]
	v_mfma_f32_16x16x32_bf16 v[40:43], v[136:139], v[204:207], v[40:43]
	v_mfma_f32_16x16x32_bf16 v[28:31], v[128:131], v[212:215], v[28:31]
	v_mfma_f32_16x16x32_bf16 v[24:27], v[136:139], v[212:215], v[24:27]
	v_mfma_f32_16x16x32_bf16 v[12:15], v[128:131], v[220:223], v[12:15]
	v_mfma_f32_16x16x32_bf16 v[8:11], v[136:139], v[220:223], v[8:11]
	v_mfma_f32_16x16x32_bf16 v[60:63], v[132:135], v[200:203], v[60:63]
	v_mfma_f32_16x16x32_bf16 v[56:59], v[140:143], v[200:203], v[56:59]
	v_mfma_f32_16x16x32_bf16 v[44:47], v[132:135], v[208:211], v[44:47]
	v_mfma_f32_16x16x32_bf16 v[40:43], v[140:143], v[208:211], v[40:43]
	v_mfma_f32_16x16x32_bf16 v[28:31], v[132:135], v[216:219], v[28:31]
	v_mfma_f32_16x16x32_bf16 v[24:27], v[140:143], v[216:219], v[24:27]
	v_mfma_f32_16x16x32_bf16 v[12:15], v[132:135], v[224:227], v[12:15]
	v_mfma_f32_16x16x32_bf16 v[8:11], v[140:143], v[224:227], v[8:11]
	v_mfma_f32_16x16x32_bf16 v[52:55], v[168:171], v[196:199], v[52:55]
	v_mfma_f32_16x16x32_bf16 v[48:51], v[176:179], v[196:199], v[48:51]
	v_mfma_f32_16x16x32_bf16 v[36:39], v[168:171], v[204:207], v[36:39]
	v_mfma_f32_16x16x32_bf16 v[32:35], v[176:179], v[204:207], v[32:35]
	v_mfma_f32_16x16x32_bf16 v[20:23], v[168:171], v[212:215], v[20:23]
	v_mfma_f32_16x16x32_bf16 v[16:19], v[176:179], v[212:215], v[16:19]
	v_mfma_f32_16x16x32_bf16 v[4:7], v[168:171], v[220:223], v[4:7]
	v_mfma_f32_16x16x32_bf16 v[0:3], v[176:179], v[220:223], v[0:3]
	v_mfma_f32_16x16x32_bf16 v[52:55], v[172:175], v[200:203], v[52:55]
	v_mfma_f32_16x16x32_bf16 v[48:51], v[180:183], v[200:203], v[48:51]
	v_mfma_f32_16x16x32_bf16 v[36:39], v[172:175], v[208:211], v[36:39]
	v_mfma_f32_16x16x32_bf16 v[32:35], v[180:183], v[208:211], v[32:35]
	v_mfma_f32_16x16x32_bf16 v[20:23], v[172:175], v[216:219], v[20:23]
	v_mfma_f32_16x16x32_bf16 v[16:19], v[180:183], v[216:219], v[16:19]
	v_mfma_f32_16x16x32_bf16 v[4:7], v[172:175], v[224:227], v[4:7]
	v_mfma_f32_16x16x32_bf16 v[0:3], v[180:183], v[224:227], v[0:3]
	s_barrier
	s_add_i32 s91, s91, 2
	s_add_u32 s8, s8, 0x100
	s_addc_u32 s9, s9, 0
	s_add_u32 s67, s67, 0x100
	s_addc_u32 s90, s90, 0
	s_cmp_gt_u32 s91, 61
	s_cbranch_scc0 .LBB0_86
	s_and_b64 vcc, exec, s[24:25]
	s_cbranch_vccz .LBB0_89
	s_barrier

; #define PG8_STAGE(bufoff, gbase, voff) do { _Pragma("unroll") for (int _i = 0; _i < 2; ++_i) \
;         __builtin_amdgcn_global_load_lds((const unsigned*)((const char*)(gbase) + (voff)[_i]), (PG8_LAS unsigned*)(lds + (bufoff) + ldsw + _i * 8192), 16, 0, 0); } while (0)
; #define PG8_LDA(dst, b, h) do { _Pragma("unroll") for (int m = 0; m < 4; ++m) _Pragma("unroll") for (int k = 0; k < 2; ++k) dst[m][k] = *(const PG8_LAS bf16x8*)(lds + PG8_SA(b, h) + aoff + m * 2048 + k * 1024); } while (0)
; #define PG8_LDB(dst, b, h) do { _Pragma("unroll") for (int n = 0; n < 2; ++n) _Pragma("unroll") for (int k = 0; k < 2; ++k) dst[n][k] = *(const PG8_LAS bf16x8*)(lds + PG8_SB(b, h) + boff + n * 2048 + k * 1024); } while (0)
; #define PG8_MMA(ai, bj, At, Bt) do { __builtin_amdgcn_s_setprio(1); _Pragma("unroll") for (int m = 0; m < 4; ++m) _Pragma("unroll") for (int n = 0; n < 2; ++n) _Pragma("unroll") for (int k = 0; k < 2; ++k) \
;         acc[ai][bj][m][n] = __builtin_amdgcn_mfma_f32_16x16x32_bf16(Bt[n][k], At[m][k], acc[ai][bj][m][n], 0, 0, 0); __builtin_amdgcn_s_setprio(0); } while (0)
; #define PG8_WAIT_V(n) asm volatile("s_waitcnt vmcnt(" #n ")" ::: "memory")
; #define PG8_WAIT_L(n) asm volatile("s_waitcnt lgkmcnt(" #n ")" ::: "memory")
; #define PG8_BAR __builtin_amdgcn_s_barrier()
; #define PG8_SCHED __builtin_amdgcn_sched_barrier(0)
; template <class Epi, class Sched, bool ALIGN_EPI = false, bool SP2 = false>
; __device__ __forceinline__ void gemm_phase(PG8_LAS unsigned char* lds, const Gemm g, const Sched& S, const Epi& E) {
;     ...
;             PG8_LDB(B0, 0, 0); PG8_LDB(B1, 0, 1); PG8_SCHED; PG8_LDA(At, 0, 0); PG8_STAGE(PG8_SA(1, 1), a1 + hstep, voffA);
;             PG8_WAIT_V(8); PG8_WAIT_L(0); PG8_BAR; PG8_MMA(0, 0, At, B0); PG8_MMA(0, 1, At, B1); PG8_BAR; PG8_SCHED;
;             PG8_LDA(At, 0, 1); PG8_STAGE(PG8_SB(0, 0), b2, voffB); PG8_STAGE(PG8_SB(0, 1), b2 + hstep, voffB); PG8_STAGE(PG8_SA(0, 0), a2, voffA);
;             PG8_WAIT_V(8); PG8_WAIT_L(0); PG8_BAR; PG8_MMA(1, 0, At, B0); PG8_MMA(1, 1, At, B1); PG8_BAR; PG8_SCHED;
.LBB0_613:
	ds_read_b128 v[76:79], v221
	ds_read_b128 v[80:83], v221 offset:1024
	ds_read_b128 v[88:91], v221 offset:2048
	ds_read_b128 v[96:99], v221 offset:3072
	ds_read_b128 v[144:147], v222
	ds_read_b128 v[148:151], v222 offset:1024
	ds_read_b128 v[152:155], v222 offset:2048
	ds_read_b128 v[156:159], v222 offset:3072
	s_add_u32 s46, s44, 0xfff00080
	s_addc_u32 s47, s45, -1
	s_cmp_eq_u32 s72, 60
	s_cselect_b32 s49, s27, s47
	s_cselect_b32 s48, s41, s46
	s_cselect_b32 s47, s25, s71
	s_cselect_b32 s46, s69, s70
	v_lshl_add_u64 v[206:207], s[44:45], 0, v[198:199]
	s_add_i32 m0, s43, 0xc000
	ds_read_b128 v[160:163], v223
	ds_read_b128 v[164:167], v223 offset:1024
	ds_read_b128 v[168:171], v223 offset:2048
	ds_read_b128 v[172:175], v223 offset:3072
	ds_read_b128 v[176:179], v223 offset:4096
	ds_read_b128 v[180:183], v223 offset:5120
	ds_read_b128 v[184:187], v223 offset:6144
	ds_read_b128 v[188:191], v223 offset:7168
	global_load_lds_dwordx4 v[206:207], off
	v_lshl_add_u64 v[206:207], s[44:45], 0, v[200:201]
	s_add_i32 m0, s43, 0xe000
	s_nop 0
	global_load_lds_dwordx4 v[206:207], off
	s_waitcnt vmcnt(8)
	s_waitcnt lgkmcnt(0)
	s_barrier
	s_waitcnt lgkmcnt(0)
	v_mfma_f32_16x16x32_bf16 v[140:143], v[76:79], v[160:163], v[140:143]
	v_mfma_f32_16x16x32_bf16 v[136:139], v[88:91], v[160:163], v[136:139]
	v_mfma_f32_16x16x32_bf16 v[124:127], v[76:79], v[168:171], v[124:127]
	v_mfma_f32_16x16x32_bf16 v[120:123], v[88:91], v[168:171], v[120:123]
	v_mfma_f32_16x16x32_bf16 v[108:111], v[76:79], v[176:179], v[108:111]
	v_mfma_f32_16x16x32_bf16 v[104:107], v[88:91], v[176:179], v[104:107]
	v_mfma_f32_16x16x32_bf16 v[84:87], v[76:79], v[184:187], v[84:87]
	v_mfma_f32_16x16x32_bf16 v[72:75], v[88:91], v[184:187], v[72:75]
	v_mfma_f32_16x16x32_bf16 v[140:143], v[80:83], v[164:167], v[140:143]
	v_mfma_f32_16x16x32_bf16 v[136:139], v[96:99], v[164:167], v[136:139]
	v_mfma_f32_16x16x32_bf16 v[124:127], v[80:83], v[172:175], v[124:127]
	v_mfma_f32_16x16x32_bf16 v[120:123], v[96:99], v[172:175], v[120:123]
	v_mfma_f32_16x16x32_bf16 v[108:111], v[80:83], v[180:183], v[108:111]
	v_mfma_f32_16x16x32_bf16 v[104:107], v[96:99], v[180:183], v[104:107]
	v_mfma_f32_16x16x32_bf16 v[84:87], v[80:83], v[188:191], v[84:87]
	v_mfma_f32_16x16x32_bf16 v[72:75], v[96:99], v[188:191], v[72:75]
	v_mfma_f32_16x16x32_bf16 v[132:135], v[144:147], v[160:163], v[132:135]
	v_mfma_f32_16x16x32_bf16 v[128:131], v[152:155], v[160:163], v[128:131]
	v_mfma_f32_16x16x32_bf16 v[116:119], v[144:147], v[168:171], v[116:119]
	v_mfma_f32_16x16x32_bf16 v[112:115], v[152:155], v[168:171], v[112:115]
	v_mfma_f32_16x16x32_bf16 v[100:103], v[144:147], v[176:179], v[100:103]
	v_mfma_f32_16x16x32_bf16 v[92:95], v[152:155], v[176:179], v[92:95]
	v_mfma_f32_16x16x32_bf16 v[68:71], v[144:147], v[184:187], v[68:71]
	v_mfma_f32_16x16x32_bf16 v[64:67], v[152:155], v[184:187], v[64:67]
	v_mfma_f32_16x16x32_bf16 v[132:135], v[148:151], v[164:167], v[132:135]
	v_mfma_f32_16x16x32_bf16 v[128:131], v[156:159], v[164:167], v[128:131]
	v_mfma_f32_16x16x32_bf16 v[116:119], v[148:151], v[172:175], v[116:119]
	v_mfma_f32_16x16x32_bf16 v[112:115], v[156:159], v[172:175], v[112:115]
	v_mfma_f32_16x16x32_bf16 v[100:103], v[148:151], v[180:183], v[100:103]
	v_mfma_f32_16x16x32_bf16 v[92:95], v[156:159], v[180:183], v[92:95]
	v_mfma_f32_16x16x32_bf16 v[68:71], v[148:151], v[188:191], v[68:71]
	v_mfma_f32_16x16x32_bf16 v[64:67], v[156:159], v[188:191], v[64:67]
	s_barrier
	s_add_i32 s73, s67, s54
	v_lshl_add_u64 v[206:207], s[46:47], 0, v[194:195]
	s_mov_b32 m0, s73
	ds_read_b128 v[160:163], v223 offset:16384
	ds_read_b128 v[164:167], v223 offset:17408
	ds_read_b128 v[168:171], v223 offset:18432
	ds_read_b128 v[172:175], v223 offset:19456
	ds_read_b128 v[176:179], v223 offset:20480
	ds_read_b128 v[180:183], v223 offset:21504
	ds_read_b128 v[184:187], v223 offset:22528
	ds_read_b128 v[188:191], v223 offset:23552
	global_load_lds_dwordx4 v[206:207], off
	s_add_i32 m0, s73, 0x2000
	s_add_u32 s74, s46, 0x100000
	v_lshl_add_u64 v[208:209], s[46:47], 0, v[196:197]
	s_addc_u32 s75, s47, 0
	s_add_i32 s73, s68, s54
	global_load_lds_dwordx4 v[208:209], off
	v_lshl_add_u64 v[210:211], s[74:75], 0, v[194:195]
	s_mov_b32 m0, s73
	v_lshl_add_u64 v[212:213], s[48:49], 0, v[196:197]
	global_load_lds_dwordx4 v[210:211], off
	v_lshl_add_u64 v[210:211], s[74:75], 0, v[196:197]
	s_add_i32 m0, s73, 0x2000
	s_nop 0
	global_load_lds_dwordx4 v[210:211], off
	v_lshl_add_u64 v[210:211], s[48:49], 0, v[194:195]
	s_mov_b32 m0, s43
	s_nop 0
	global_load_lds_dwordx4 v[210:211], off
	s_mov_b32 m0, s56
	s_nop 0
	global_load_lds_dwordx4 v[212:213], off
	s_waitcnt vmcnt(8)
	s_waitcnt lgkmcnt(0)
	s_barrier
; #define PG8_STAGE(bufoff, gbase, voff) do { _Pragma("unroll") for (int _i = 0; _i < 2; ++_i) \
;         __builtin_amdgcn_global_load_lds((const unsigned*)((const char*)(gbase) + (voff)[_i]), (PG8_LAS unsigned*)(lds + (bufoff) + ldsw + _i * 8192), 16, 0, 0); } while (0)
; #define PG8_LDA(dst, b, h) do { _Pragma("unroll") for (int m = 0; m < 4; ++m) _Pragma("unroll") for (int k = 0; k < 2; ++k) dst[m][k] = *(const PG8_LAS bf16x8*)(lds + PG8_SA(b, h) + aoff + m * 2048 + k * 1024); } while (0)
; #define PG8_LDB(dst, b, h) do { _Pragma("unroll") for (int n = 0; n < 2; ++n) _Pragma("unroll") for (int k = 0; k < 2; ++k) dst[n][k] = *(const PG8_LAS bf16x8*)(lds + PG8_SB(b, h) + boff + n * 2048 + k * 1024); } while (0)
; #define PG8_MMA(ai, bj, At, Bt) do { __builtin_amdgcn_s_setprio(1); _Pragma("unroll") for (int m = 0; m < 4; ++m) _Pragma("unroll") for (int n = 0; n < 2; ++n) _Pragma("unroll") for (int k = 0; k < 2; ++k) \
;         acc[ai][bj][m][n] = __builtin_amdgcn_mfma_f32_16x16x32_bf16(Bt[n][k], At[m][k], acc[ai][bj][m][n], 0, 0, 0); __builtin_amdgcn_s_setprio(0); } while (0)
; #define PG8_WAIT_V(n) asm volatile("s_waitcnt vmcnt(" #n ")" ::: "memory")
; #define PG8_WAIT_L(n) asm volatile("s_waitcnt lgkmcnt(" #n ")" ::: "memory")
; #define PG8_BAR __builtin_amdgcn_s_barrier()
; #define PG8_SCHED __builtin_amdgcn_sched_barrier(0)
; template <class Epi, class Sched, bool ALIGN_EPI = false, bool SP2 = false>
; __device__ __forceinline__ void gemm_phase(PG8_LAS unsigned char* lds, const Gemm g, const Sched& S, const Epi& E) {
;     ...
;             PG8_WAIT_V(8); PG8_WAIT_L(0); PG8_BAR; PG8_MMA(1, 0, At, B0); PG8_MMA(1, 1, At, B1); PG8_BAR; PG8_SCHED;
;             PG8_LDB(B0, 1, 0); PG8_LDB(B1, 1, 1); PG8_SCHED; PG8_LDA(At, 1, 0); PG8_STAGE(PG8_SA(0, 1), a2 + hstep, voffA);
;             PG8_WAIT_V(8); PG8_WAIT_L(0); PG8_BAR; PG8_MMA(0, 0, At, B0); PG8_MMA(0, 1, At, B1); PG8_BAR; PG8_SCHED;
	s_waitcnt lgkmcnt(0)
	v_mfma_f32_16x16x32_bf16 v[60:63], v[76:79], v[160:163], v[60:63]
	v_mfma_f32_16x16x32_bf16 v[56:59], v[88:91], v[160:163], v[56:59]
	v_mfma_f32_16x16x32_bf16 v[44:47], v[76:79], v[168:171], v[44:47]
	v_mfma_f32_16x16x32_bf16 v[40:43], v[88:91], v[168:171], v[40:43]
	v_mfma_f32_16x16x32_bf16 v[28:31], v[76:79], v[176:179], v[28:31]
	v_mfma_f32_16x16x32_bf16 v[24:27], v[88:91], v[176:179], v[24:27]
	v_mfma_f32_16x16x32_bf16 v[12:15], v[76:79], v[184:187], v[12:15]
	v_mfma_f32_16x16x32_bf16 v[8:11], v[88:91], v[184:187], v[8:11]
	v_mfma_f32_16x16x32_bf16 v[60:63], v[80:83], v[164:167], v[60:63]
	v_mfma_f32_16x16x32_bf16 v[56:59], v[96:99], v[164:167], v[56:59]
	v_mfma_f32_16x16x32_bf16 v[44:47], v[80:83], v[172:175], v[44:47]
	v_mfma_f32_16x16x32_bf16 v[40:43], v[96:99], v[172:175], v[40:43]
	v_mfma_f32_16x16x32_bf16 v[28:31], v[80:83], v[180:183], v[28:31]
	v_mfma_f32_16x16x32_bf16 v[24:27], v[96:99], v[180:183], v[24:27]
	v_mfma_f32_16x16x32_bf16 v[12:15], v[80:83], v[188:191], v[12:15]
	v_mfma_f32_16x16x32_bf16 v[8:11], v[96:99], v[188:191], v[8:11]
	v_mfma_f32_16x16x32_bf16 v[52:55], v[144:147], v[160:163], v[52:55]
	v_mfma_f32_16x16x32_bf16 v[48:51], v[152:155], v[160:163], v[48:51]
	v_mfma_f32_16x16x32_bf16 v[36:39], v[144:147], v[168:171], v[36:39]
	v_mfma_f32_16x16x32_bf16 v[32:35], v[152:155], v[168:171], v[32:35]
	v_mfma_f32_16x16x32_bf16 v[20:23], v[144:147], v[176:179], v[20:23]
	v_mfma_f32_16x16x32_bf16 v[16:19], v[152:155], v[176:179], v[16:19]
	v_mfma_f32_16x16x32_bf16 v[4:7], v[144:147], v[184:187], v[4:7]
	v_mfma_f32_16x16x32_bf16 v[0:3], v[152:155], v[184:187], v[0:3]
	v_mfma_f32_16x16x32_bf16 v[52:55], v[148:151], v[164:167], v[52:55]
	v_mfma_f32_16x16x32_bf16 v[48:51], v[156:159], v[164:167], v[48:51]
	v_mfma_f32_16x16x32_bf16 v[36:39], v[148:151], v[172:175], v[36:39]
	v_mfma_f32_16x16x32_bf16 v[32:35], v[156:159], v[172:175], v[32:35]
	v_mfma_f32_16x16x32_bf16 v[20:23], v[148:151], v[180:183], v[20:23]
	v_mfma_f32_16x16x32_bf16 v[16:19], v[156:159], v[180:183], v[16:19]
	v_mfma_f32_16x16x32_bf16 v[4:7], v[148:151], v[188:191], v[4:7]
	v_mfma_f32_16x16x32_bf16 v[0:3], v[156:159], v[188:191], v[0:3]
	s_barrier
	s_add_i32 s73, 0, 0x18000
	s_add_i32 s74, 0, 0x1c000
	v_add_u32_e32 v96, s73, v219
	v_add_u32_e32 v156, s74, v219
	ds_read_b128 v[76:79], v96
	ds_read_b128 v[80:83], v96 offset:1024
	ds_read_b128 v[88:91], v96 offset:2048
	ds_read_b128 v[96:99], v96 offset:3072
	ds_read_b128 v[144:147], v156
	ds_read_b128 v[148:151], v156 offset:1024
	ds_read_b128 v[152:155], v156 offset:2048
	ds_read_b128 v[156:159], v156 offset:3072
	s_add_u32 s48, s48, 0x100000
	s_addc_u32 s49, s49, 0
	s_mov_b32 m0, s58
	v_lshl_add_u64 v[214:215], s[48:49], 0, v[194:195]
	ds_read_b128 v[160:163], v223 offset:32768
	ds_read_b128 v[164:167], v223 offset:33792
	ds_read_b128 v[168:171], v223 offset:34816
	ds_read_b128 v[172:175], v223 offset:35840
	ds_read_b128 v[176:179], v223 offset:36864
	ds_read_b128 v[180:183], v223 offset:37888
	ds_read_b128 v[184:187], v223 offset:38912
	ds_read_b128 v[188:191], v223 offset:39936
	global_load_lds_dwordx4 v[214:215], off
	v_lshl_add_u64 v[214:215], s[48:49], 0, v[196:197]
	s_mov_b32 m0, s60
	s_nop 0
	global_load_lds_dwordx4 v[214:215], off
	s_waitcnt vmcnt(8)
	s_waitcnt lgkmcnt(0)
	s_barrier
	s_waitcnt lgkmcnt(0)
	v_mfma_f32_16x16x32_bf16 v[140:143], v[76:79], v[160:163], v[140:143]
	v_mfma_f32_16x16x32_bf16 v[136:139], v[88:91], v[160:163], v[136:139]
	v_mfma_f32_16x16x32_bf16 v[124:127], v[76:79], v[168:171], v[124:127]
	v_mfma_f32_16x16x32_bf16 v[120:123], v[88:91], v[168:171], v[120:123]
	v_mfma_f32_16x16x32_bf16 v[108:111], v[76:79], v[176:179], v[108:111]
	v_mfma_f32_16x16x32_bf16 v[104:107], v[88:91], v[176:179], v[104:107]
	v_mfma_f32_16x16x32_bf16 v[84:87], v[76:79], v[184:187], v[84:87]
	v_mfma_f32_16x16x32_bf16 v[72:75], v[88:91], v[184:187], v[72:75]
	v_mfma_f32_16x16x32_bf16 v[140:143], v[80:83], v[164:167], v[140:143]
	v_mfma_f32_16x16x32_bf16 v[136:139], v[96:99], v[164:167], v[136:139]
	v_mfma_f32_16x16x32_bf16 v[124:127], v[80:83], v[172:175], v[124:127]
	v_mfma_f32_16x16x32_bf16 v[120:123], v[96:99], v[172:175], v[120:123]
	v_mfma_f32_16x16x32_bf16 v[108:111], v[80:83], v[180:183], v[108:111]
	v_mfma_f32_16x16x32_bf16 v[104:107], v[96:99], v[180:183], v[104:107]
	v_mfma_f32_16x16x32_bf16 v[84:87], v[80:83], v[188:191], v[84:87]
	v_mfma_f32_16x16x32_bf16 v[72:75], v[96:99], v[188:191], v[72:75]
	v_mfma_f32_16x16x32_bf16 v[132:135], v[144:147], v[160:163], v[132:135]
	v_mfma_f32_16x16x32_bf16 v[128:131], v[152:155], v[160:163], v[128:131]
	v_mfma_f32_16x16x32_bf16 v[116:119], v[144:147], v[168:171], v[116:119]
	v_mfma_f32_16x16x32_bf16 v[112:115], v[152:155], v[168:171], v[112:115]
	v_mfma_f32_16x16x32_bf16 v[100:103], v[144:147], v[176:179], v[100:103]
	v_mfma_f32_16x16x32_bf16 v[92:95], v[152:155], v[176:179], v[92:95]
	v_mfma_f32_16x16x32_bf16 v[68:71], v[144:147], v[184:187], v[68:71]
	v_mfma_f32_16x16x32_bf16 v[64:67], v[152:155], v[184:187], v[64:67]
	v_mfma_f32_16x16x32_bf16 v[132:135], v[148:151], v[164:167], v[132:135]
	v_mfma_f32_16x16x32_bf16 v[128:131], v[156:159], v[164:167], v[128:131]
	v_mfma_f32_16x16x32_bf16 v[116:119], v[148:151], v[172:175], v[116:119]
	v_mfma_f32_16x16x32_bf16 v[112:115], v[156:159], v[172:175], v[112:115]
	v_mfma_f32_16x16x32_bf16 v[100:103], v[148:151], v[180:183], v[100:103]
	v_mfma_f32_16x16x32_bf16 v[92:95], v[156:159], v[180:183], v[92:95]
	v_mfma_f32_16x16x32_bf16 v[68:71], v[148:151], v[188:191], v[68:71]
	v_mfma_f32_16x16x32_bf16 v[64:67], v[156:159], v[188:191], v[64:67]
	s_barrier
; #define PG8_STAGE(bufoff, gbase, voff) do { _Pragma("unroll") for (int _i = 0; _i < 2; ++_i) \
;         __builtin_amdgcn_global_load_lds((const unsigned*)((const char*)(gbase) + (voff)[_i]), (PG8_LAS unsigned*)(lds + (bufoff) + ldsw + _i * 8192), 16, 0, 0); } while (0)
; #define PG8_LDA(dst, b, h) do { _Pragma("unroll") for (int m = 0; m < 4; ++m) _Pragma("unroll") for (int k = 0; k < 2; ++k) dst[m][k] = *(const PG8_LAS bf16x8*)(lds + PG8_SA(b, h) + aoff + m * 2048 + k * 1024); } while (0)
; #define PG8_MMA(ai, bj, At, Bt) do { __builtin_amdgcn_s_setprio(1); _Pragma("unroll") for (int m = 0; m < 4; ++m) _Pragma("unroll") for (int n = 0; n < 2; ++n) _Pragma("unroll") for (int k = 0; k < 2; ++k) \
;         acc[ai][bj][m][n] = __builtin_amdgcn_mfma_f32_16x16x32_bf16(Bt[n][k], At[m][k], acc[ai][bj][m][n], 0, 0, 0); __builtin_amdgcn_s_setprio(0); } while (0)
; #define PG8_WAIT_V(n) asm volatile("s_waitcnt vmcnt(" #n ")" ::: "memory")
; #define PG8_WAIT_L(n) asm volatile("s_waitcnt lgkmcnt(" #n ")" ::: "memory")
; #define PG8_BAR __builtin_amdgcn_s_barrier()
; #define PG8_SCHED __builtin_amdgcn_sched_barrier(0)
; template <class Epi, class Sched, bool ALIGN_EPI = false, bool SP2 = false>
; __device__ __forceinline__ void gemm_phase(PG8_LAS unsigned char* lds, const Gemm g, const Sched& S, const Epi& E) {
;     ...
;         for (int t = 0; t < nt; t += 2) {
;             const bool last = (t == nt - 2);
;             const char* a1 = cA + (size_t)(t + 1) * kstep;
;             const char* a2 = last ? nA : cA + (size_t)(t + 2) * kstep; const char* b2 = last ? nB : cB + (size_t)(t + 2) * kstep;
;     ...
;             PG8_LDA(At, 1, 1); PG8_STAGE(PG8_SB(1, 0), b3, voffB); PG8_STAGE(PG8_SB(1, 1), b3 + hstep, voffB); PG8_STAGE(PG8_SA(1, 0), a3, voffA);
;             PG8_WAIT_V(8); PG8_WAIT_L(0); PG8_BAR; PG8_MMA(1, 0, At, B0); PG8_MMA(1, 1, At, B1); PG8_BAR; PG8_SCHED;
	s_add_i32 s48, s73, s54
	v_lshl_add_u64 v[206:207], v[206:207], 0, s[20:21]
	s_mov_b32 m0, s48
	ds_read_b128 v[160:163], v223 offset:49152
	ds_read_b128 v[164:167], v223 offset:50176
	ds_read_b128 v[168:171], v223 offset:51200
	ds_read_b128 v[172:175], v223 offset:52224
	ds_read_b128 v[176:179], v223 offset:53248
	ds_read_b128 v[180:183], v223 offset:54272
	ds_read_b128 v[184:187], v223 offset:55296
	ds_read_b128 v[188:191], v223 offset:56320
	global_load_lds_dwordx4 v[206:207], off
	s_add_i32 m0, s48, 0x2000
	s_add_u32 s46, s46, 0x100080
	v_lshl_add_u64 v[206:207], v[208:209], 0, s[20:21]
	s_addc_u32 s47, s47, 0
	s_add_i32 s48, s74, s54
	global_load_lds_dwordx4 v[206:207], off
	v_lshl_add_u64 v[206:207], s[46:47], 0, v[194:195]
	s_mov_b32 m0, s48
	s_nop 0
	global_load_lds_dwordx4 v[206:207], off
	v_lshl_add_u64 v[206:207], s[46:47], 0, v[196:197]
	s_add_i32 m0, s48, 0x2000
	s_nop 0
	global_load_lds_dwordx4 v[206:207], off
	v_lshl_add_u64 v[206:207], v[210:211], 0, s[20:21]
	s_mov_b32 m0, s64
	s_nop 0
	global_load_lds_dwordx4 v[206:207], off
	v_lshl_add_u64 v[206:207], v[212:213], 0, s[20:21]
	s_mov_b32 m0, s65
	s_nop 0
	global_load_lds_dwordx4 v[206:207], off
	s_waitcnt vmcnt(8)
	s_waitcnt lgkmcnt(0)
	s_barrier
	s_waitcnt lgkmcnt(0)
	v_mfma_f32_16x16x32_bf16 v[60:63], v[76:79], v[160:163], v[60:63]
	v_mfma_f32_16x16x32_bf16 v[56:59], v[88:91], v[160:163], v[56:59]
	v_mfma_f32_16x16x32_bf16 v[44:47], v[76:79], v[168:171], v[44:47]
	v_mfma_f32_16x16x32_bf16 v[40:43], v[88:91], v[168:171], v[40:43]
	v_mfma_f32_16x16x32_bf16 v[28:31], v[76:79], v[176:179], v[28:31]
	v_mfma_f32_16x16x32_bf16 v[24:27], v[88:91], v[176:179], v[24:27]
	v_mfma_f32_16x16x32_bf16 v[12:15], v[76:79], v[184:187], v[12:15]
	v_mfma_f32_16x16x32_bf16 v[8:11], v[88:91], v[184:187], v[8:11]
	v_mfma_f32_16x16x32_bf16 v[60:63], v[80:83], v[164:167], v[60:63]
	v_mfma_f32_16x16x32_bf16 v[56:59], v[96:99], v[164:167], v[56:59]
	v_mfma_f32_16x16x32_bf16 v[44:47], v[80:83], v[172:175], v[44:47]
	v_mfma_f32_16x16x32_bf16 v[40:43], v[96:99], v[172:175], v[40:43]
	v_mfma_f32_16x16x32_bf16 v[28:31], v[80:83], v[180:183], v[28:31]
	v_mfma_f32_16x16x32_bf16 v[24:27], v[96:99], v[180:183], v[24:27]
	v_mfma_f32_16x16x32_bf16 v[12:15], v[80:83], v[188:191], v[12:15]
	v_mfma_f32_16x16x32_bf16 v[8:11], v[96:99], v[188:191], v[8:11]
	v_mfma_f32_16x16x32_bf16 v[52:55], v[144:147], v[160:163], v[52:55]
	v_mfma_f32_16x16x32_bf16 v[48:51], v[152:155], v[160:163], v[48:51]
	v_mfma_f32_16x16x32_bf16 v[36:39], v[144:147], v[168:171], v[36:39]
	v_mfma_f32_16x16x32_bf16 v[32:35], v[152:155], v[168:171], v[32:35]
	v_mfma_f32_16x16x32_bf16 v[20:23], v[144:147], v[176:179], v[20:23]
	v_mfma_f32_16x16x32_bf16 v[16:19], v[152:155], v[176:179], v[16:19]
	v_mfma_f32_16x16x32_bf16 v[4:7], v[144:147], v[184:187], v[4:7]
	v_mfma_f32_16x16x32_bf16 v[0:3], v[152:155], v[184:187], v[0:3]
	v_mfma_f32_16x16x32_bf16 v[52:55], v[148:151], v[164:167], v[52:55]
	v_mfma_f32_16x16x32_bf16 v[48:51], v[156:159], v[164:167], v[48:51]
	v_mfma_f32_16x16x32_bf16 v[36:39], v[148:151], v[172:175], v[36:39]
	v_mfma_f32_16x16x32_bf16 v[32:35], v[156:159], v[172:175], v[32:35]
	v_mfma_f32_16x16x32_bf16 v[20:23], v[148:151], v[180:183], v[20:23]
	v_mfma_f32_16x16x32_bf16 v[16:19], v[156:159], v[180:183], v[16:19]
	v_mfma_f32_16x16x32_bf16 v[4:7], v[148:151], v[188:191], v[4:7]
	v_mfma_f32_16x16x32_bf16 v[0:3], v[156:159], v[188:191], v[0:3]
	s_barrier
	s_add_i32 s72, s72, 2
	s_add_u32 s44, s44, 0x100
	s_addc_u32 s45, s45, 0
	s_add_u32 s70, s70, 0x100
	s_addc_u32 s71, s71, 0
	s_cmp_gt_u32 s72, 61
	s_cbranch_scc0 .LBB0_613
	s_and_b64 vcc, exec, s[22:23]
	s_cbranch_vccz .LBB0_616
	s_barrier

; #define PG8_STAGE(bufoff, gbase, voff) do { _Pragma("unroll") for (int _i = 0; _i < 2; ++_i) \
;         __builtin_amdgcn_global_load_lds((const unsigned*)((const char*)(gbase) + (voff)[_i]), (PG8_LAS unsigned*)(lds + (bufoff) + ldsw + _i * 8192), 16, 0, 0); } while (0)
; #define PG8_LDA(dst, b, h) do { _Pragma("unroll") for (int m = 0; m < 4; ++m) _Pragma("unroll") for (int k = 0; k < 2; ++k) dst[m][k] = *(const PG8_LAS bf16x8*)(lds + PG8_SA(b, h) + aoff + m * 2048 + k * 1024); } while (0)
; #define PG8_LDB(dst, b, h) do { _Pragma("unroll") for (int n = 0; n < 2; ++n) _Pragma("unroll") for (int k = 0; k < 2; ++k) dst[n][k] = *(const PG8_LAS bf16x8*)(lds + PG8_SB(b, h) + boff + n * 2048 + k * 1024); } while (0)
; #define PG8_MMA(ai, bj, At, Bt) do { __builtin_amdgcn_s_setprio(1); _Pragma("unroll") for (int m = 0; m < 4; ++m) _Pragma("unroll") for (int n = 0; n < 2; ++n) _Pragma("unroll") for (int k = 0; k < 2; ++k) \
;         acc[ai][bj][m][n] = __builtin_amdgcn_mfma_f32_16x16x32_bf16(Bt[n][k], At[m][k], acc[ai][bj][m][n], 0, 0, 0); __builtin_amdgcn_s_setprio(0); } while (0)
; #define PG8_WAIT_V(n) asm volatile("s_waitcnt vmcnt(" #n ")" ::: "memory")
; #define PG8_WAIT_L(n) asm volatile("s_waitcnt lgkmcnt(" #n ")" ::: "memory")
; #define PG8_BAR __builtin_amdgcn_s_barrier()
; #define PG8_SCHED __builtin_amdgcn_sched_barrier(0)
; template <class Epi, class Sched, bool ALIGN_EPI = false, bool SP2 = false>
; __device__ __forceinline__ void gemm_phase(PG8_LAS unsigned char* lds, const Gemm g, const Sched& S, const Epi& E) {
;     ...
;             PG8_LDB(B0, 0, 0); PG8_LDB(B1, 0, 1); PG8_SCHED; PG8_LDA(At, 0, 0); PG8_STAGE(PG8_SA(1, 1), a1 + hstep, voffA);
;             PG8_WAIT_V(8); PG8_WAIT_L(0); PG8_BAR; PG8_MMA(0, 0, At, B0); PG8_MMA(0, 1, At, B1); PG8_BAR; PG8_SCHED;
;             PG8_LDA(At, 0, 1); PG8_STAGE(PG8_SB(0, 0), b2, voffB); PG8_STAGE(PG8_SB(0, 1), b2 + hstep, voffB); PG8_STAGE(PG8_SA(0, 0), a2, voffA);
;             PG8_WAIT_V(8); PG8_WAIT_L(0); PG8_BAR; PG8_MMA(1, 0, At, B0); PG8_MMA(1, 1, At, B1); PG8_BAR; PG8_SCHED;
.LBB0_699:
	ds_read_b128 v[128:131], v208
	ds_read_b128 v[132:135], v208 offset:1024
	ds_read_b128 v[136:139], v208 offset:2048
	ds_read_b128 v[140:143], v208 offset:3072
	ds_read_b128 v[168:171], v209
	ds_read_b128 v[172:175], v209 offset:1024
	ds_read_b128 v[176:179], v209 offset:2048
	ds_read_b128 v[180:183], v209 offset:3072
	s_add_u32 s8, s6, 0xfff00080
	s_addc_u32 s9, s7, -1
	s_cmp_eq_u32 s94, 60
	s_cselect_b32 s13, s14, s9
	s_cselect_b32 s12, s15, s8
	s_cselect_b32 s9, s67, s93
	s_cselect_b32 s8, s69, s92
	v_lshl_add_u64 v[228:229], s[6:7], 0, v[160:161]
	s_add_i32 m0, s75, 0xc000
	ds_read_b128 v[184:187], v210
	ds_read_b128 v[188:191], v210 offset:1024
	ds_read_b128 v[194:197], v210 offset:2048
	ds_read_b128 v[198:201], v210 offset:3072
	ds_read_b128 v[202:205], v210 offset:4096
	ds_read_b128 v[216:219], v210 offset:5120
	ds_read_b128 v[220:223], v210 offset:6144
	ds_read_b128 v[224:227], v210 offset:7168
	global_load_lds_dwordx4 v[228:229], off
	v_lshl_add_u64 v[228:229], s[6:7], 0, v[162:163]
	s_add_i32 m0, s75, 0xe000
	s_nop 0
	global_load_lds_dwordx4 v[228:229], off
	s_waitcnt vmcnt(8)
	s_waitcnt lgkmcnt(0)
	s_barrier
	s_waitcnt lgkmcnt(0)
	v_mfma_f32_16x16x32_bf16 v[124:127], v[128:131], v[184:187], v[124:127]
	v_mfma_f32_16x16x32_bf16 v[120:123], v[136:139], v[184:187], v[120:123]
	v_mfma_f32_16x16x32_bf16 v[108:111], v[128:131], v[194:197], v[108:111]
	v_mfma_f32_16x16x32_bf16 v[104:107], v[136:139], v[194:197], v[104:107]
	v_mfma_f32_16x16x32_bf16 v[92:95], v[128:131], v[202:205], v[92:95]
	v_mfma_f32_16x16x32_bf16 v[88:91], v[136:139], v[202:205], v[88:91]
	v_mfma_f32_16x16x32_bf16 v[76:79], v[128:131], v[220:223], v[76:79]
	v_mfma_f32_16x16x32_bf16 v[72:75], v[136:139], v[220:223], v[72:75]
	v_mfma_f32_16x16x32_bf16 v[124:127], v[132:135], v[188:191], v[124:127]
	v_mfma_f32_16x16x32_bf16 v[120:123], v[140:143], v[188:191], v[120:123]
	v_mfma_f32_16x16x32_bf16 v[108:111], v[132:135], v[198:201], v[108:111]
	v_mfma_f32_16x16x32_bf16 v[104:107], v[140:143], v[198:201], v[104:107]
	v_mfma_f32_16x16x32_bf16 v[92:95], v[132:135], v[216:219], v[92:95]
	v_mfma_f32_16x16x32_bf16 v[88:91], v[140:143], v[216:219], v[88:91]
	v_mfma_f32_16x16x32_bf16 v[76:79], v[132:135], v[224:227], v[76:79]
	v_mfma_f32_16x16x32_bf16 v[72:75], v[140:143], v[224:227], v[72:75]
	v_mfma_f32_16x16x32_bf16 v[116:119], v[168:171], v[184:187], v[116:119]
	v_mfma_f32_16x16x32_bf16 v[112:115], v[176:179], v[184:187], v[112:115]
	v_mfma_f32_16x16x32_bf16 v[100:103], v[168:171], v[194:197], v[100:103]
	v_mfma_f32_16x16x32_bf16 v[96:99], v[176:179], v[194:197], v[96:99]
	v_mfma_f32_16x16x32_bf16 v[84:87], v[168:171], v[202:205], v[84:87]
	v_mfma_f32_16x16x32_bf16 v[80:83], v[176:179], v[202:205], v[80:83]
	v_mfma_f32_16x16x32_bf16 v[68:71], v[168:171], v[220:223], v[68:71]
	v_mfma_f32_16x16x32_bf16 v[64:67], v[176:179], v[220:223], v[64:67]
	v_mfma_f32_16x16x32_bf16 v[116:119], v[172:175], v[188:191], v[116:119]
	v_mfma_f32_16x16x32_bf16 v[112:115], v[180:183], v[188:191], v[112:115]
	v_mfma_f32_16x16x32_bf16 v[100:103], v[172:175], v[198:201], v[100:103]
	v_mfma_f32_16x16x32_bf16 v[96:99], v[180:183], v[198:201], v[96:99]
	v_mfma_f32_16x16x32_bf16 v[84:87], v[172:175], v[216:219], v[84:87]
	v_mfma_f32_16x16x32_bf16 v[80:83], v[180:183], v[216:219], v[80:83]
	v_mfma_f32_16x16x32_bf16 v[68:71], v[172:175], v[224:227], v[68:71]
	v_mfma_f32_16x16x32_bf16 v[64:67], v[180:183], v[224:227], v[64:67]
	s_barrier
	s_add_i32 s95, s88, s76
	v_lshl_add_u64 v[228:229], s[8:9], 0, v[146:147]
	s_mov_b32 m0, s95
	ds_read_b128 v[184:187], v210 offset:16384
	ds_read_b128 v[188:191], v210 offset:17408
	ds_read_b128 v[194:197], v210 offset:18432
	ds_read_b128 v[198:201], v210 offset:19456
	ds_read_b128 v[202:205], v210 offset:20480
	ds_read_b128 v[216:219], v210 offset:21504
	ds_read_b128 v[220:223], v210 offset:22528
	ds_read_b128 v[224:227], v210 offset:23552
	global_load_lds_dwordx4 v[228:229], off
	s_add_i32 m0, s95, 0x2000
	s_add_u32 s96, s8, 0x100000
	v_lshl_add_u64 v[230:231], s[8:9], 0, v[150:151]
	s_addc_u32 s97, s9, 0
	s_add_i32 s95, s89, s76
	global_load_lds_dwordx4 v[230:231], off
	v_lshl_add_u64 v[232:233], s[96:97], 0, v[146:147]
	s_mov_b32 m0, s95
	v_lshl_add_u64 v[234:235], s[12:13], 0, v[148:149]
	global_load_lds_dwordx4 v[232:233], off
	v_lshl_add_u64 v[232:233], s[96:97], 0, v[150:151]
	s_add_i32 m0, s95, 0x2000
	s_nop 0
	global_load_lds_dwordx4 v[232:233], off
	v_lshl_add_u64 v[232:233], s[12:13], 0, v[144:145]
	s_mov_b32 m0, s75
	s_nop 0
	global_load_lds_dwordx4 v[232:233], off
	s_mov_b32 m0, s77
	s_nop 0
	global_load_lds_dwordx4 v[234:235], off
	s_waitcnt vmcnt(8)
	s_waitcnt lgkmcnt(0)
	s_barrier
; #define PG8_STAGE(bufoff, gbase, voff) do { _Pragma("unroll") for (int _i = 0; _i < 2; ++_i) \
;         __builtin_amdgcn_global_load_lds((const unsigned*)((const char*)(gbase) + (voff)[_i]), (PG8_LAS unsigned*)(lds + (bufoff) + ldsw + _i * 8192), 16, 0, 0); } while (0)
; #define PG8_LDA(dst, b, h) do { _Pragma("unroll") for (int m = 0; m < 4; ++m) _Pragma("unroll") for (int k = 0; k < 2; ++k) dst[m][k] = *(const PG8_LAS bf16x8*)(lds + PG8_SA(b, h) + aoff + m * 2048 + k * 1024); } while (0)
; #define PG8_LDB(dst, b, h) do { _Pragma("unroll") for (int n = 0; n < 2; ++n) _Pragma("unroll") for (int k = 0; k < 2; ++k) dst[n][k] = *(const PG8_LAS bf16x8*)(lds + PG8_SB(b, h) + boff + n * 2048 + k * 1024); } while (0)
; #define PG8_MMA(ai, bj, At, Bt) do { __builtin_amdgcn_s_setprio(1); _Pragma("unroll") for (int m = 0; m < 4; ++m) _Pragma("unroll") for (int n = 0; n < 2; ++n) _Pragma("unroll") for (int k = 0; k < 2; ++k) \
;         acc[ai][bj][m][n] = __builtin_amdgcn_mfma_f32_16x16x32_bf16(Bt[n][k], At[m][k], acc[ai][bj][m][n], 0, 0, 0); __builtin_amdgcn_s_setprio(0); } while (0)
; #define PG8_WAIT_V(n) asm volatile("s_waitcnt vmcnt(" #n ")" ::: "memory")
; #define PG8_WAIT_L(n) asm volatile("s_waitcnt lgkmcnt(" #n ")" ::: "memory")
; #define PG8_BAR __builtin_amdgcn_s_barrier()
; #define PG8_SCHED __builtin_amdgcn_sched_barrier(0)
; template <class Epi, class Sched, bool ALIGN_EPI = false, bool SP2 = false>
; __device__ __forceinline__ void gemm_phase(PG8_LAS unsigned char* lds, const Gemm g, const Sched& S, const Epi& E) {
;     ...
;             PG8_WAIT_V(8); PG8_WAIT_L(0); PG8_BAR; PG8_MMA(1, 0, At, B0); PG8_MMA(1, 1, At, B1); PG8_BAR; PG8_SCHED;
;             PG8_LDB(B0, 1, 0); PG8_LDB(B1, 1, 1); PG8_SCHED; PG8_LDA(At, 1, 0); PG8_STAGE(PG8_SA(0, 1), a2 + hstep, voffA);
;             PG8_WAIT_V(8); PG8_WAIT_L(0); PG8_BAR; PG8_MMA(0, 0, At, B0); PG8_MMA(0, 1, At, B1); PG8_BAR; PG8_SCHED;
	s_waitcnt lgkmcnt(0)
	v_mfma_f32_16x16x32_bf16 v[60:63], v[128:131], v[184:187], v[60:63]
	v_mfma_f32_16x16x32_bf16 v[56:59], v[136:139], v[184:187], v[56:59]
	v_mfma_f32_16x16x32_bf16 v[44:47], v[128:131], v[194:197], v[44:47]
	v_mfma_f32_16x16x32_bf16 v[40:43], v[136:139], v[194:197], v[40:43]
	v_mfma_f32_16x16x32_bf16 v[28:31], v[128:131], v[202:205], v[28:31]
	v_mfma_f32_16x16x32_bf16 v[24:27], v[136:139], v[202:205], v[24:27]
	v_mfma_f32_16x16x32_bf16 v[12:15], v[128:131], v[220:223], v[12:15]
	v_mfma_f32_16x16x32_bf16 v[8:11], v[136:139], v[220:223], v[8:11]
	v_mfma_f32_16x16x32_bf16 v[60:63], v[132:135], v[188:191], v[60:63]
	v_mfma_f32_16x16x32_bf16 v[56:59], v[140:143], v[188:191], v[56:59]
	v_mfma_f32_16x16x32_bf16 v[44:47], v[132:135], v[198:201], v[44:47]
	v_mfma_f32_16x16x32_bf16 v[40:43], v[140:143], v[198:201], v[40:43]
	v_mfma_f32_16x16x32_bf16 v[28:31], v[132:135], v[216:219], v[28:31]
	v_mfma_f32_16x16x32_bf16 v[24:27], v[140:143], v[216:219], v[24:27]
	v_mfma_f32_16x16x32_bf16 v[12:15], v[132:135], v[224:227], v[12:15]
	v_mfma_f32_16x16x32_bf16 v[8:11], v[140:143], v[224:227], v[8:11]
	v_mfma_f32_16x16x32_bf16 v[52:55], v[168:171], v[184:187], v[52:55]
	v_mfma_f32_16x16x32_bf16 v[48:51], v[176:179], v[184:187], v[48:51]
	v_mfma_f32_16x16x32_bf16 v[36:39], v[168:171], v[194:197], v[36:39]
	v_mfma_f32_16x16x32_bf16 v[32:35], v[176:179], v[194:197], v[32:35]
	v_mfma_f32_16x16x32_bf16 v[20:23], v[168:171], v[202:205], v[20:23]
	v_mfma_f32_16x16x32_bf16 v[16:19], v[176:179], v[202:205], v[16:19]
	v_mfma_f32_16x16x32_bf16 v[4:7], v[168:171], v[220:223], v[4:7]
	v_mfma_f32_16x16x32_bf16 v[0:3], v[176:179], v[220:223], v[0:3]
	v_mfma_f32_16x16x32_bf16 v[52:55], v[172:175], v[188:191], v[52:55]
	v_mfma_f32_16x16x32_bf16 v[48:51], v[180:183], v[188:191], v[48:51]
	v_mfma_f32_16x16x32_bf16 v[36:39], v[172:175], v[198:201], v[36:39]
	v_mfma_f32_16x16x32_bf16 v[32:35], v[180:183], v[198:201], v[32:35]
	v_mfma_f32_16x16x32_bf16 v[20:23], v[172:175], v[216:219], v[20:23]
	v_mfma_f32_16x16x32_bf16 v[16:19], v[180:183], v[216:219], v[16:19]
	v_mfma_f32_16x16x32_bf16 v[4:7], v[172:175], v[224:227], v[4:7]
	v_mfma_f32_16x16x32_bf16 v[0:3], v[180:183], v[224:227], v[0:3]
	s_barrier
	s_add_i32 s95, 0, 0x18000
	s_add_i32 s96, 0, 0x1c000
	v_add_u32_e32 v140, s95, v207
	v_add_u32_e32 v152, s96, v207
	ds_read_b128 v[128:131], v140
	ds_read_b128 v[132:135], v140 offset:1024
	ds_read_b128 v[136:139], v140 offset:2048
	ds_read_b128 v[140:143], v140 offset:3072
	ds_read_b128 v[168:171], v152
	ds_read_b128 v[172:175], v152 offset:1024
	ds_read_b128 v[176:179], v152 offset:2048
	ds_read_b128 v[180:183], v152 offset:3072
	s_add_u32 s12, s12, 0x100000
	s_addc_u32 s13, s13, 0
	s_mov_b32 m0, s78
	v_lshl_add_u64 v[236:237], s[12:13], 0, v[144:145]
	ds_read_b128 v[184:187], v210 offset:32768
	ds_read_b128 v[188:191], v210 offset:33792
	ds_read_b128 v[194:197], v210 offset:34816
	ds_read_b128 v[198:201], v210 offset:35840
	ds_read_b128 v[202:205], v210 offset:36864
	ds_read_b128 v[216:219], v210 offset:37888
	ds_read_b128 v[220:223], v210 offset:38912
	ds_read_b128 v[224:227], v210 offset:39936
	global_load_lds_dwordx4 v[236:237], off
	v_lshl_add_u64 v[236:237], s[12:13], 0, v[148:149]
	s_mov_b32 m0, s79
	s_nop 0
	global_load_lds_dwordx4 v[236:237], off
	s_waitcnt vmcnt(8)
	s_waitcnt lgkmcnt(0)
	s_barrier
	s_waitcnt lgkmcnt(0)
	v_mfma_f32_16x16x32_bf16 v[124:127], v[128:131], v[184:187], v[124:127]
	v_mfma_f32_16x16x32_bf16 v[120:123], v[136:139], v[184:187], v[120:123]
	v_mfma_f32_16x16x32_bf16 v[108:111], v[128:131], v[194:197], v[108:111]
	v_mfma_f32_16x16x32_bf16 v[104:107], v[136:139], v[194:197], v[104:107]
	v_mfma_f32_16x16x32_bf16 v[92:95], v[128:131], v[202:205], v[92:95]
	v_mfma_f32_16x16x32_bf16 v[88:91], v[136:139], v[202:205], v[88:91]
	v_mfma_f32_16x16x32_bf16 v[76:79], v[128:131], v[220:223], v[76:79]
	v_mfma_f32_16x16x32_bf16 v[72:75], v[136:139], v[220:223], v[72:75]
	v_mfma_f32_16x16x32_bf16 v[124:127], v[132:135], v[188:191], v[124:127]
	v_mfma_f32_16x16x32_bf16 v[120:123], v[140:143], v[188:191], v[120:123]
	v_mfma_f32_16x16x32_bf16 v[108:111], v[132:135], v[198:201], v[108:111]
	v_mfma_f32_16x16x32_bf16 v[104:107], v[140:143], v[198:201], v[104:107]
	v_mfma_f32_16x16x32_bf16 v[92:95], v[132:135], v[216:219], v[92:95]
	v_mfma_f32_16x16x32_bf16 v[88:91], v[140:143], v[216:219], v[88:91]
	v_mfma_f32_16x16x32_bf16 v[76:79], v[132:135], v[224:227], v[76:79]
	v_mfma_f32_16x16x32_bf16 v[72:75], v[140:143], v[224:227], v[72:75]
	v_mfma_f32_16x16x32_bf16 v[116:119], v[168:171], v[184:187], v[116:119]
	v_mfma_f32_16x16x32_bf16 v[112:115], v[176:179], v[184:187], v[112:115]
	v_mfma_f32_16x16x32_bf16 v[100:103], v[168:171], v[194:197], v[100:103]
	v_mfma_f32_16x16x32_bf16 v[96:99], v[176:179], v[194:197], v[96:99]
	v_mfma_f32_16x16x32_bf16 v[84:87], v[168:171], v[202:205], v[84:87]
	v_mfma_f32_16x16x32_bf16 v[80:83], v[176:179], v[202:205], v[80:83]
	v_mfma_f32_16x16x32_bf16 v[68:71], v[168:171], v[220:223], v[68:71]
	v_mfma_f32_16x16x32_bf16 v[64:67], v[176:179], v[220:223], v[64:67]
	v_mfma_f32_16x16x32_bf16 v[116:119], v[172:175], v[188:191], v[116:119]
	v_mfma_f32_16x16x32_bf16 v[112:115], v[180:183], v[188:191], v[112:115]
	v_mfma_f32_16x16x32_bf16 v[100:103], v[172:175], v[198:201], v[100:103]
	v_mfma_f32_16x16x32_bf16 v[96:99], v[180:183], v[198:201], v[96:99]
	v_mfma_f32_16x16x32_bf16 v[84:87], v[172:175], v[216:219], v[84:87]
	v_mfma_f32_16x16x32_bf16 v[80:83], v[180:183], v[216:219], v[80:83]
	v_mfma_f32_16x16x32_bf16 v[68:71], v[172:175], v[224:227], v[68:71]
	v_mfma_f32_16x16x32_bf16 v[64:67], v[180:183], v[224:227], v[64:67]
	s_barrier
; #define PG8_STAGE(bufoff, gbase, voff) do { _Pragma("unroll") for (int _i = 0; _i < 2; ++_i) \
;         __builtin_amdgcn_global_load_lds((const unsigned*)((const char*)(gbase) + (voff)[_i]), (PG8_LAS unsigned*)(lds + (bufoff) + ldsw + _i * 8192), 16, 0, 0); } while (0)
; #define PG8_LDA(dst, b, h) do { _Pragma("unroll") for (int m = 0; m < 4; ++m) _Pragma("unroll") for (int k = 0; k < 2; ++k) dst[m][k] = *(const PG8_LAS bf16x8*)(lds + PG8_SA(b, h) + aoff + m * 2048 + k * 1024); } while (0)
; #define PG8_MMA(ai, bj, At, Bt) do { __builtin_amdgcn_s_setprio(1); _Pragma("unroll") for (int m = 0; m < 4; ++m) _Pragma("unroll") for (int n = 0; n < 2; ++n) _Pragma("unroll") for (int k = 0; k < 2; ++k) \
;         acc[ai][bj][m][n] = __builtin_amdgcn_mfma_f32_16x16x32_bf16(Bt[n][k], At[m][k], acc[ai][bj][m][n], 0, 0, 0); __builtin_amdgcn_s_setprio(0); } while (0)
; #define PG8_WAIT_V(n) asm volatile("s_waitcnt vmcnt(" #n ")" ::: "memory")
; #define PG8_WAIT_L(n) asm volatile("s_waitcnt lgkmcnt(" #n ")" ::: "memory")
; #define PG8_BAR __builtin_amdgcn_s_barrier()
; #define PG8_SCHED __builtin_amdgcn_sched_barrier(0)
; template <class Epi, class Sched, bool ALIGN_EPI = false, bool SP2 = false>
; __device__ __forceinline__ void gemm_phase(PG8_LAS unsigned char* lds, const Gemm g, const Sched& S, const Epi& E) {
;     ...
;         for (int t = 0; t < nt; t += 2) {
;             const bool last = (t == nt - 2);
;             const char* a1 = cA + (size_t)(t + 1) * kstep;
;             const char* a2 = last ? nA : cA + (size_t)(t + 2) * kstep; const char* b2 = last ? nB : cB + (size_t)(t + 2) * kstep;
;     ...
;             PG8_LDA(At, 1, 1); PG8_STAGE(PG8_SB(1, 0), b3, voffB); PG8_STAGE(PG8_SB(1, 1), b3 + hstep, voffB); PG8_STAGE(PG8_SA(1, 0), a3, voffA);
;             PG8_WAIT_V(8); PG8_WAIT_L(0); PG8_BAR; PG8_MMA(1, 0, At, B0); PG8_MMA(1, 1, At, B1); PG8_BAR; PG8_SCHED;
	s_add_i32 s12, s95, s76
	v_lshl_add_u64 v[228:229], v[228:229], 0, s[24:25]
	s_mov_b32 m0, s12
	ds_read_b128 v[184:187], v210 offset:49152
	ds_read_b128 v[188:191], v210 offset:50176
	ds_read_b128 v[194:197], v210 offset:51200
	ds_read_b128 v[198:201], v210 offset:52224
	ds_read_b128 v[202:205], v210 offset:53248
	ds_read_b128 v[216:219], v210 offset:54272
	ds_read_b128 v[220:223], v210 offset:55296
	ds_read_b128 v[224:227], v210 offset:56320
	global_load_lds_dwordx4 v[228:229], off
	s_add_i32 m0, s12, 0x2000
	s_add_u32 s8, s8, 0x100080
	v_lshl_add_u64 v[228:229], v[230:231], 0, s[24:25]
	s_addc_u32 s9, s9, 0
	s_add_i32 s12, s96, s76
	global_load_lds_dwordx4 v[228:229], off
	v_lshl_add_u64 v[228:229], s[8:9], 0, v[146:147]
	s_mov_b32 m0, s12
	s_nop 0
	global_load_lds_dwordx4 v[228:229], off
	v_lshl_add_u64 v[228:229], s[8:9], 0, v[150:151]
	s_add_i32 m0, s12, 0x2000
	s_nop 0
	global_load_lds_dwordx4 v[228:229], off
	v_lshl_add_u64 v[228:229], v[232:233], 0, s[24:25]
	s_mov_b32 m0, s85
	s_nop 0
	global_load_lds_dwordx4 v[228:229], off
	v_lshl_add_u64 v[228:229], v[234:235], 0, s[24:25]
	s_mov_b32 m0, s86
	s_nop 0
	global_load_lds_dwordx4 v[228:229], off
	s_waitcnt vmcnt(8)
	s_waitcnt lgkmcnt(0)
	s_barrier
	s_waitcnt lgkmcnt(0)
	v_mfma_f32_16x16x32_bf16 v[60:63], v[128:131], v[184:187], v[60:63]
	v_mfma_f32_16x16x32_bf16 v[56:59], v[136:139], v[184:187], v[56:59]
	v_mfma_f32_16x16x32_bf16 v[44:47], v[128:131], v[194:197], v[44:47]
	v_mfma_f32_16x16x32_bf16 v[40:43], v[136:139], v[194:197], v[40:43]
	v_mfma_f32_16x16x32_bf16 v[28:31], v[128:131], v[202:205], v[28:31]
	v_mfma_f32_16x16x32_bf16 v[24:27], v[136:139], v[202:205], v[24:27]
	v_mfma_f32_16x16x32_bf16 v[12:15], v[128:131], v[220:223], v[12:15]
	v_mfma_f32_16x16x32_bf16 v[8:11], v[136:139], v[220:223], v[8:11]
	v_mfma_f32_16x16x32_bf16 v[60:63], v[132:135], v[188:191], v[60:63]
	v_mfma_f32_16x16x32_bf16 v[56:59], v[140:143], v[188:191], v[56:59]
	v_mfma_f32_16x16x32_bf16 v[44:47], v[132:135], v[198:201], v[44:47]
	v_mfma_f32_16x16x32_bf16 v[40:43], v[140:143], v[198:201], v[40:43]
	v_mfma_f32_16x16x32_bf16 v[28:31], v[132:135], v[216:219], v[28:31]
	v_mfma_f32_16x16x32_bf16 v[24:27], v[140:143], v[216:219], v[24:27]
	v_mfma_f32_16x16x32_bf16 v[12:15], v[132:135], v[224:227], v[12:15]
	v_mfma_f32_16x16x32_bf16 v[8:11], v[140:143], v[224:227], v[8:11]
	v_mfma_f32_16x16x32_bf16 v[52:55], v[168:171], v[184:187], v[52:55]
	v_mfma_f32_16x16x32_bf16 v[48:51], v[176:179], v[184:187], v[48:51]
	v_mfma_f32_16x16x32_bf16 v[36:39], v[168:171], v[194:197], v[36:39]
	v_mfma_f32_16x16x32_bf16 v[32:35], v[176:179], v[194:197], v[32:35]
	v_mfma_f32_16x16x32_bf16 v[20:23], v[168:171], v[202:205], v[20:23]
	v_mfma_f32_16x16x32_bf16 v[16:19], v[176:179], v[202:205], v[16:19]
	v_mfma_f32_16x16x32_bf16 v[4:7], v[168:171], v[220:223], v[4:7]
	v_mfma_f32_16x16x32_bf16 v[0:3], v[176:179], v[220:223], v[0:3]
	v_mfma_f32_16x16x32_bf16 v[52:55], v[172:175], v[188:191], v[52:55]
	v_mfma_f32_16x16x32_bf16 v[48:51], v[180:183], v[188:191], v[48:51]
	v_mfma_f32_16x16x32_bf16 v[36:39], v[172:175], v[198:201], v[36:39]
	v_mfma_f32_16x16x32_bf16 v[32:35], v[180:183], v[198:201], v[32:35]
	v_mfma_f32_16x16x32_bf16 v[20:23], v[172:175], v[216:219], v[20:23]
	v_mfma_f32_16x16x32_bf16 v[16:19], v[180:183], v[216:219], v[16:19]
	v_mfma_f32_16x16x32_bf16 v[4:7], v[172:175], v[224:227], v[4:7]
	v_mfma_f32_16x16x32_bf16 v[0:3], v[180:183], v[224:227], v[0:3]
	s_barrier
	s_add_i32 s94, s94, 2
	s_add_u32 s6, s6, 0x100
	s_addc_u32 s7, s7, 0
	s_add_u32 s92, s92, 0x100
	s_addc_u32 s93, s93, 0
	s_cmp_gt_u32 s94, 61
	s_cbranch_scc0 .LBB0_699
	s_and_b64 vcc, exec, s[26:27]
	s_cbranch_vccz .LBB0_702
	s_barrier

; #define PG8_STAGE(bufoff, gbase, voff) do { _Pragma("unroll") for (int _i = 0; _i < 2; ++_i) \
;         __builtin_amdgcn_global_load_lds((const unsigned*)((const char*)(gbase) + (voff)[_i]), (PG8_LAS unsigned*)(lds + (bufoff) + ldsw + _i * 8192), 16, 0, 0); } while (0)
; #define PG8_LDA(dst, b, h) do { _Pragma("unroll") for (int m = 0; m < 4; ++m) _Pragma("unroll") for (int k = 0; k < 2; ++k) dst[m][k] = *(const PG8_LAS bf16x8*)(lds + PG8_SA(b, h) + aoff + m * 2048 + k * 1024); } while (0)
; #define PG8_LDB(dst, b, h) do { _Pragma("unroll") for (int n = 0; n < 2; ++n) _Pragma("unroll") for (int k = 0; k < 2; ++k) dst[n][k] = *(const PG8_LAS bf16x8*)(lds + PG8_SB(b, h) + boff + n * 2048 + k * 1024); } while (0)
; #define PG8_MMA(ai, bj, At, Bt) do { __builtin_amdgcn_s_setprio(1); _Pragma("unroll") for (int m = 0; m < 4; ++m) _Pragma("unroll") for (int n = 0; n < 2; ++n) _Pragma("unroll") for (int k = 0; k < 2; ++k) \
;         acc[ai][bj][m][n] = __builtin_amdgcn_mfma_f32_16x16x32_bf16(Bt[n][k], At[m][k], acc[ai][bj][m][n], 0, 0, 0); __builtin_amdgcn_s_setprio(0); } while (0)
; #define PG8_WAIT_V(n) asm volatile("s_waitcnt vmcnt(" #n ")" ::: "memory")
; #define PG8_WAIT_L(n) asm volatile("s_waitcnt lgkmcnt(" #n ")" ::: "memory")
; #define PG8_BAR __builtin_amdgcn_s_barrier()
; #define PG8_SCHED __builtin_amdgcn_sched_barrier(0)
; template <class Epi, class Sched, bool ALIGN_EPI = false, bool SP2 = false>
; __device__ __forceinline__ void gemm_phase(PG8_LAS unsigned char* lds, const Gemm g, const Sched& S, const Epi& E) {
;     ...
;             PG8_LDB(B0, 0, 0); PG8_LDB(B1, 0, 1); PG8_SCHED; PG8_LDA(At, 0, 0); PG8_STAGE(PG8_SA(1, 1), a1 + hstep, voffA);
;             PG8_WAIT_V(8); PG8_WAIT_L(0); PG8_BAR; PG8_MMA(0, 0, At, B0); PG8_MMA(0, 1, At, B1); PG8_BAR; PG8_SCHED;
;             PG8_LDA(At, 0, 1); PG8_STAGE(PG8_SB(0, 0), b2, voffB); PG8_STAGE(PG8_SB(0, 1), b2 + hstep, voffB); PG8_STAGE(PG8_SA(0, 0), a2, voffA);
;             PG8_WAIT_V(8); PG8_WAIT_L(0); PG8_BAR; PG8_MMA(1, 0, At, B0); PG8_MMA(1, 1, At, B1); PG8_BAR; PG8_SCHED;
.LBB0_1224:
	ds_read_b128 v[140:143], v149
	ds_read_b128 v[152:155], v149 offset:1024
	ds_read_b128 v[156:159], v149 offset:2048
	ds_read_b128 v[160:163], v149 offset:3072
	ds_read_b128 v[164:167], v150
	ds_read_b128 v[168:171], v150 offset:1024
	ds_read_b128 v[172:175], v150 offset:2048
	ds_read_b128 v[176:179], v150 offset:3072
	s_add_u32 s36, s26, 0xfff00080
	s_addc_u32 s37, s27, -1
	s_cmp_eq_u32 s64, 60
	s_cselect_b32 s39, s19, s37
	s_cselect_b32 s38, s60, s36
	s_cselect_b32 s37, s17, s63
	s_cselect_b32 s36, s61, s62
	v_lshl_add_u64 v[144:145], s[26:27], 0, v[132:133]
	s_add_i32 m0, s25, 0xc000
	ds_read_b128 v[180:183], v151
	ds_read_b128 v[184:187], v151 offset:1024
	ds_read_b128 v[188:191], v151 offset:2048
	ds_read_b128 v[194:197], v151 offset:3072
	ds_read_b128 v[198:201], v151 offset:4096
	ds_read_b128 v[202:205], v151 offset:5120
	ds_read_b128 v[206:209], v151 offset:6144
	ds_read_b128 v[210:213], v151 offset:7168
	global_load_lds_dwordx4 v[144:145], off
	v_lshl_add_u64 v[144:145], s[26:27], 0, v[134:135]
	s_add_i32 m0, s25, 0xe000
	s_nop 0
	global_load_lds_dwordx4 v[144:145], off
	s_waitcnt vmcnt(8)
	s_waitcnt lgkmcnt(0)
	s_barrier
	s_waitcnt lgkmcnt(0)
	v_mfma_f32_16x16x32_bf16 v[124:127], v[140:143], v[180:183], v[124:127]
	v_mfma_f32_16x16x32_bf16 v[120:123], v[156:159], v[180:183], v[120:123]
	v_mfma_f32_16x16x32_bf16 v[116:119], v[140:143], v[188:191], v[116:119]
	v_mfma_f32_16x16x32_bf16 v[112:115], v[156:159], v[188:191], v[112:115]
	v_mfma_f32_16x16x32_bf16 v[108:111], v[140:143], v[198:201], v[108:111]
	v_mfma_f32_16x16x32_bf16 v[100:103], v[156:159], v[198:201], v[100:103]
	v_mfma_f32_16x16x32_bf16 v[92:95], v[140:143], v[206:209], v[92:95]
	v_mfma_f32_16x16x32_bf16 v[80:83], v[156:159], v[206:209], v[80:83]
	v_mfma_f32_16x16x32_bf16 v[124:127], v[152:155], v[184:187], v[124:127]
	v_mfma_f32_16x16x32_bf16 v[120:123], v[160:163], v[184:187], v[120:123]
	v_mfma_f32_16x16x32_bf16 v[116:119], v[152:155], v[194:197], v[116:119]
	v_mfma_f32_16x16x32_bf16 v[112:115], v[160:163], v[194:197], v[112:115]
	v_mfma_f32_16x16x32_bf16 v[108:111], v[152:155], v[202:205], v[108:111]
	v_mfma_f32_16x16x32_bf16 v[100:103], v[160:163], v[202:205], v[100:103]
	v_mfma_f32_16x16x32_bf16 v[92:95], v[152:155], v[210:213], v[92:95]
	v_mfma_f32_16x16x32_bf16 v[80:83], v[160:163], v[210:213], v[80:83]
	v_mfma_f32_16x16x32_bf16 v[104:107], v[164:167], v[180:183], v[104:107]
	v_mfma_f32_16x16x32_bf16 v[96:99], v[172:175], v[180:183], v[96:99]
	v_mfma_f32_16x16x32_bf16 v[88:91], v[164:167], v[188:191], v[88:91]
	v_mfma_f32_16x16x32_bf16 v[84:87], v[172:175], v[188:191], v[84:87]
	v_mfma_f32_16x16x32_bf16 v[76:79], v[164:167], v[198:201], v[76:79]
	v_mfma_f32_16x16x32_bf16 v[72:75], v[172:175], v[198:201], v[72:75]
	v_mfma_f32_16x16x32_bf16 v[68:71], v[164:167], v[206:209], v[68:71]
	v_mfma_f32_16x16x32_bf16 v[64:67], v[172:175], v[206:209], v[64:67]
	v_mfma_f32_16x16x32_bf16 v[104:107], v[168:171], v[184:187], v[104:107]
	v_mfma_f32_16x16x32_bf16 v[96:99], v[176:179], v[184:187], v[96:99]
	v_mfma_f32_16x16x32_bf16 v[88:91], v[168:171], v[194:197], v[88:91]
	v_mfma_f32_16x16x32_bf16 v[84:87], v[176:179], v[194:197], v[84:87]
	v_mfma_f32_16x16x32_bf16 v[76:79], v[168:171], v[202:205], v[76:79]
	v_mfma_f32_16x16x32_bf16 v[72:75], v[176:179], v[202:205], v[72:75]
	v_mfma_f32_16x16x32_bf16 v[68:71], v[168:171], v[210:213], v[68:71]
	v_mfma_f32_16x16x32_bf16 v[64:67], v[176:179], v[210:213], v[64:67]
	s_barrier
	s_add_i32 s65, s54, s44
	v_lshl_add_u64 v[144:145], s[36:37], 0, v[130:131]
	s_mov_b32 m0, s65
	ds_read_b128 v[180:183], v151 offset:16384
	ds_read_b128 v[184:187], v151 offset:17408
	ds_read_b128 v[188:191], v151 offset:18432
	ds_read_b128 v[194:197], v151 offset:19456
	ds_read_b128 v[198:201], v151 offset:20480
	ds_read_b128 v[202:205], v151 offset:21504
	ds_read_b128 v[206:209], v151 offset:22528
	ds_read_b128 v[210:213], v151 offset:23552
	global_load_lds_dwordx4 v[144:145], off
	s_add_i32 m0, s65, 0x2000
	s_add_u32 s66, s36, 0x100000
	v_lshl_add_u64 v[214:215], s[36:37], 0, v[128:129]
	s_addc_u32 s67, s37, 0
	s_add_i32 s65, s56, s44
	global_load_lds_dwordx4 v[214:215], off
	v_lshl_add_u64 v[216:217], s[66:67], 0, v[130:131]
	s_mov_b32 m0, s65
	v_lshl_add_u64 v[218:219], s[38:39], 0, v[128:129]
	global_load_lds_dwordx4 v[216:217], off
	v_lshl_add_u64 v[216:217], s[66:67], 0, v[128:129]
	s_add_i32 m0, s65, 0x2000
	s_nop 0
	global_load_lds_dwordx4 v[216:217], off
	v_lshl_add_u64 v[216:217], s[38:39], 0, v[130:131]
	s_mov_b32 m0, s25
	s_nop 0
	global_load_lds_dwordx4 v[216:217], off
	s_mov_b32 m0, s46
	s_nop 0
	global_load_lds_dwordx4 v[218:219], off
	s_waitcnt vmcnt(8)
	s_waitcnt lgkmcnt(0)
	s_barrier
; #define PG8_STAGE(bufoff, gbase, voff) do { _Pragma("unroll") for (int _i = 0; _i < 2; ++_i) \
;         __builtin_amdgcn_global_load_lds((const unsigned*)((const char*)(gbase) + (voff)[_i]), (PG8_LAS unsigned*)(lds + (bufoff) + ldsw + _i * 8192), 16, 0, 0); } while (0)
; #define PG8_LDA(dst, b, h) do { _Pragma("unroll") for (int m = 0; m < 4; ++m) _Pragma("unroll") for (int k = 0; k < 2; ++k) dst[m][k] = *(const PG8_LAS bf16x8*)(lds + PG8_SA(b, h) + aoff + m * 2048 + k * 1024); } while (0)
; #define PG8_LDB(dst, b, h) do { _Pragma("unroll") for (int n = 0; n < 2; ++n) _Pragma("unroll") for (int k = 0; k < 2; ++k) dst[n][k] = *(const PG8_LAS bf16x8*)(lds + PG8_SB(b, h) + boff + n * 2048 + k * 1024); } while (0)
; #define PG8_MMA(ai, bj, At, Bt) do { __builtin_amdgcn_s_setprio(1); _Pragma("unroll") for (int m = 0; m < 4; ++m) _Pragma("unroll") for (int n = 0; n < 2; ++n) _Pragma("unroll") for (int k = 0; k < 2; ++k) \
;         acc[ai][bj][m][n] = __builtin_amdgcn_mfma_f32_16x16x32_bf16(Bt[n][k], At[m][k], acc[ai][bj][m][n], 0, 0, 0); __builtin_amdgcn_s_setprio(0); } while (0)
; #define PG8_WAIT_V(n) asm volatile("s_waitcnt vmcnt(" #n ")" ::: "memory")
; #define PG8_WAIT_L(n) asm volatile("s_waitcnt lgkmcnt(" #n ")" ::: "memory")
; #define PG8_BAR __builtin_amdgcn_s_barrier()
; #define PG8_SCHED __builtin_amdgcn_sched_barrier(0)
; template <class Epi, class Sched, bool ALIGN_EPI = false, bool SP2 = false>
; __device__ __forceinline__ void gemm_phase(PG8_LAS unsigned char* lds, const Gemm g, const Sched& S, const Epi& E) {
;     ...
;             PG8_WAIT_V(8); PG8_WAIT_L(0); PG8_BAR; PG8_MMA(1, 0, At, B0); PG8_MMA(1, 1, At, B1); PG8_BAR; PG8_SCHED;
;             PG8_LDB(B0, 1, 0); PG8_LDB(B1, 1, 1); PG8_SCHED; PG8_LDA(At, 1, 0); PG8_STAGE(PG8_SA(0, 1), a2 + hstep, voffA);
;             PG8_WAIT_V(8); PG8_WAIT_L(0); PG8_BAR; PG8_MMA(0, 0, At, B0); PG8_MMA(0, 1, At, B1); PG8_BAR; PG8_SCHED;
	s_waitcnt lgkmcnt(0)
	v_mfma_f32_16x16x32_bf16 v[60:63], v[140:143], v[180:183], v[60:63]
	v_mfma_f32_16x16x32_bf16 v[56:59], v[156:159], v[180:183], v[56:59]
	v_mfma_f32_16x16x32_bf16 v[52:55], v[140:143], v[188:191], v[52:55]
	v_mfma_f32_16x16x32_bf16 v[48:51], v[156:159], v[188:191], v[48:51]
	v_mfma_f32_16x16x32_bf16 v[44:47], v[140:143], v[198:201], v[44:47]
	v_mfma_f32_16x16x32_bf16 v[36:39], v[156:159], v[198:201], v[36:39]
	v_mfma_f32_16x16x32_bf16 v[28:31], v[140:143], v[206:209], v[28:31]
	v_mfma_f32_16x16x32_bf16 v[8:11], v[156:159], v[206:209], v[8:11]
	v_mfma_f32_16x16x32_bf16 v[60:63], v[152:155], v[184:187], v[60:63]
	v_mfma_f32_16x16x32_bf16 v[56:59], v[160:163], v[184:187], v[56:59]
	v_mfma_f32_16x16x32_bf16 v[52:55], v[152:155], v[194:197], v[52:55]
	v_mfma_f32_16x16x32_bf16 v[48:51], v[160:163], v[194:197], v[48:51]
	v_mfma_f32_16x16x32_bf16 v[44:47], v[152:155], v[202:205], v[44:47]
	v_mfma_f32_16x16x32_bf16 v[36:39], v[160:163], v[202:205], v[36:39]
	v_mfma_f32_16x16x32_bf16 v[28:31], v[152:155], v[210:213], v[28:31]
	v_mfma_f32_16x16x32_bf16 v[8:11], v[160:163], v[210:213], v[8:11]
	v_mfma_f32_16x16x32_bf16 v[40:43], v[164:167], v[180:183], v[40:43]
	v_mfma_f32_16x16x32_bf16 v[32:35], v[172:175], v[180:183], v[32:35]
	v_mfma_f32_16x16x32_bf16 v[24:27], v[164:167], v[188:191], v[24:27]
	v_mfma_f32_16x16x32_bf16 v[20:23], v[172:175], v[188:191], v[20:23]
	v_mfma_f32_16x16x32_bf16 v[16:19], v[164:167], v[198:201], v[16:19]
	v_mfma_f32_16x16x32_bf16 v[12:15], v[172:175], v[198:201], v[12:15]
	v_mfma_f32_16x16x32_bf16 v[4:7], v[164:167], v[206:209], v[4:7]
	v_mfma_f32_16x16x32_bf16 v[0:3], v[172:175], v[206:209], v[0:3]
	v_mfma_f32_16x16x32_bf16 v[40:43], v[168:171], v[184:187], v[40:43]
	v_mfma_f32_16x16x32_bf16 v[32:35], v[176:179], v[184:187], v[32:35]
	v_mfma_f32_16x16x32_bf16 v[24:27], v[168:171], v[194:197], v[24:27]
	v_mfma_f32_16x16x32_bf16 v[20:23], v[176:179], v[194:197], v[20:23]
	v_mfma_f32_16x16x32_bf16 v[16:19], v[168:171], v[202:205], v[16:19]
	v_mfma_f32_16x16x32_bf16 v[12:15], v[176:179], v[202:205], v[12:15]
	v_mfma_f32_16x16x32_bf16 v[4:7], v[168:171], v[210:213], v[4:7]
	v_mfma_f32_16x16x32_bf16 v[0:3], v[176:179], v[210:213], v[0:3]
	s_barrier
	s_add_i32 s65, 0, 0x18000
	s_add_i32 s66, 0, 0x1c000
	v_add_u32_e32 v160, s65, v147
	v_add_u32_e32 v176, s66, v147
	ds_read_b128 v[140:143], v160
	ds_read_b128 v[152:155], v160 offset:1024
	ds_read_b128 v[156:159], v160 offset:2048
	ds_read_b128 v[160:163], v160 offset:3072
	ds_read_b128 v[164:167], v176
	ds_read_b128 v[168:171], v176 offset:1024
	ds_read_b128 v[172:175], v176 offset:2048
	ds_read_b128 v[176:179], v176 offset:3072
	s_add_u32 s38, s38, 0x100000
	s_addc_u32 s39, s39, 0
	s_mov_b32 m0, s47
	v_lshl_add_u64 v[220:221], s[38:39], 0, v[130:131]
	ds_read_b128 v[180:183], v151 offset:32768
	ds_read_b128 v[184:187], v151 offset:33792
	ds_read_b128 v[188:191], v151 offset:34816
	ds_read_b128 v[194:197], v151 offset:35840
	ds_read_b128 v[198:201], v151 offset:36864
	ds_read_b128 v[202:205], v151 offset:37888
	ds_read_b128 v[206:209], v151 offset:38912
	ds_read_b128 v[210:213], v151 offset:39936
	global_load_lds_dwordx4 v[220:221], off
	v_lshl_add_u64 v[220:221], s[38:39], 0, v[128:129]
	s_mov_b32 m0, s48
	s_nop 0
	global_load_lds_dwordx4 v[220:221], off
	s_waitcnt vmcnt(8)
	s_waitcnt lgkmcnt(0)
	s_barrier
	s_waitcnt lgkmcnt(0)
	v_mfma_f32_16x16x32_bf16 v[124:127], v[140:143], v[180:183], v[124:127]
	v_mfma_f32_16x16x32_bf16 v[120:123], v[156:159], v[180:183], v[120:123]
	v_mfma_f32_16x16x32_bf16 v[116:119], v[140:143], v[188:191], v[116:119]
	v_mfma_f32_16x16x32_bf16 v[112:115], v[156:159], v[188:191], v[112:115]
	v_mfma_f32_16x16x32_bf16 v[108:111], v[140:143], v[198:201], v[108:111]
	v_mfma_f32_16x16x32_bf16 v[100:103], v[156:159], v[198:201], v[100:103]
	v_mfma_f32_16x16x32_bf16 v[92:95], v[140:143], v[206:209], v[92:95]
	v_mfma_f32_16x16x32_bf16 v[80:83], v[156:159], v[206:209], v[80:83]
	v_mfma_f32_16x16x32_bf16 v[124:127], v[152:155], v[184:187], v[124:127]
	v_mfma_f32_16x16x32_bf16 v[120:123], v[160:163], v[184:187], v[120:123]
	v_mfma_f32_16x16x32_bf16 v[116:119], v[152:155], v[194:197], v[116:119]
	v_mfma_f32_16x16x32_bf16 v[112:115], v[160:163], v[194:197], v[112:115]
	v_mfma_f32_16x16x32_bf16 v[108:111], v[152:155], v[202:205], v[108:111]
	v_mfma_f32_16x16x32_bf16 v[100:103], v[160:163], v[202:205], v[100:103]
	v_mfma_f32_16x16x32_bf16 v[92:95], v[152:155], v[210:213], v[92:95]
	v_mfma_f32_16x16x32_bf16 v[80:83], v[160:163], v[210:213], v[80:83]
	v_mfma_f32_16x16x32_bf16 v[104:107], v[164:167], v[180:183], v[104:107]
	v_mfma_f32_16x16x32_bf16 v[96:99], v[172:175], v[180:183], v[96:99]
	v_mfma_f32_16x16x32_bf16 v[88:91], v[164:167], v[188:191], v[88:91]
	v_mfma_f32_16x16x32_bf16 v[84:87], v[172:175], v[188:191], v[84:87]
	v_mfma_f32_16x16x32_bf16 v[76:79], v[164:167], v[198:201], v[76:79]
	v_mfma_f32_16x16x32_bf16 v[72:75], v[172:175], v[198:201], v[72:75]
	v_mfma_f32_16x16x32_bf16 v[68:71], v[164:167], v[206:209], v[68:71]
	v_mfma_f32_16x16x32_bf16 v[64:67], v[172:175], v[206:209], v[64:67]
	v_mfma_f32_16x16x32_bf16 v[104:107], v[168:171], v[184:187], v[104:107]
	v_mfma_f32_16x16x32_bf16 v[96:99], v[176:179], v[184:187], v[96:99]
	v_mfma_f32_16x16x32_bf16 v[88:91], v[168:171], v[194:197], v[88:91]
	v_mfma_f32_16x16x32_bf16 v[84:87], v[176:179], v[194:197], v[84:87]
	v_mfma_f32_16x16x32_bf16 v[76:79], v[168:171], v[202:205], v[76:79]
	v_mfma_f32_16x16x32_bf16 v[72:75], v[176:179], v[202:205], v[72:75]
	v_mfma_f32_16x16x32_bf16 v[68:71], v[168:171], v[210:213], v[68:71]
	v_mfma_f32_16x16x32_bf16 v[64:67], v[176:179], v[210:213], v[64:67]
	s_barrier
; #define PG8_STAGE(bufoff, gbase, voff) do { _Pragma("unroll") for (int _i = 0; _i < 2; ++_i) \
;         __builtin_amdgcn_global_load_lds((const unsigned*)((const char*)(gbase) + (voff)[_i]), (PG8_LAS unsigned*)(lds + (bufoff) + ldsw + _i * 8192), 16, 0, 0); } while (0)
; #define PG8_LDA(dst, b, h) do { _Pragma("unroll") for (int m = 0; m < 4; ++m) _Pragma("unroll") for (int k = 0; k < 2; ++k) dst[m][k] = *(const PG8_LAS bf16x8*)(lds + PG8_SA(b, h) + aoff + m * 2048 + k * 1024); } while (0)
; #define PG8_MMA(ai, bj, At, Bt) do { __builtin_amdgcn_s_setprio(1); _Pragma("unroll") for (int m = 0; m < 4; ++m) _Pragma("unroll") for (int n = 0; n < 2; ++n) _Pragma("unroll") for (int k = 0; k < 2; ++k) \
;         acc[ai][bj][m][n] = __builtin_amdgcn_mfma_f32_16x16x32_bf16(Bt[n][k], At[m][k], acc[ai][bj][m][n], 0, 0, 0); __builtin_amdgcn_s_setprio(0); } while (0)
; #define PG8_WAIT_V(n) asm volatile("s_waitcnt vmcnt(" #n ")" ::: "memory")
; #define PG8_WAIT_L(n) asm volatile("s_waitcnt lgkmcnt(" #n ")" ::: "memory")
; #define PG8_BAR __builtin_amdgcn_s_barrier()
; #define PG8_SCHED __builtin_amdgcn_sched_barrier(0)
; template <class Epi, class Sched, bool ALIGN_EPI = false, bool SP2 = false>
; __device__ __forceinline__ void gemm_phase(PG8_LAS unsigned char* lds, const Gemm g, const Sched& S, const Epi& E) {
;     ...
;         for (int t = 0; t < nt; t += 2) {
;             const bool last = (t == nt - 2);
;             const char* a1 = cA + (size_t)(t + 1) * kstep;
;             const char* a2 = last ? nA : cA + (size_t)(t + 2) * kstep; const char* b2 = last ? nB : cB + (size_t)(t + 2) * kstep;
;     ...
;             PG8_LDA(At, 1, 1); PG8_STAGE(PG8_SB(1, 0), b3, voffB); PG8_STAGE(PG8_SB(1, 1), b3 + hstep, voffB); PG8_STAGE(PG8_SA(1, 0), a3, voffA);
;             PG8_WAIT_V(8); PG8_WAIT_L(0); PG8_BAR; PG8_MMA(1, 0, At, B0); PG8_MMA(1, 1, At, B1); PG8_BAR; PG8_SCHED;
	s_add_i32 s38, s65, s44
	v_lshl_add_u64 v[144:145], v[144:145], 0, s[12:13]
	s_mov_b32 m0, s38
	ds_read_b128 v[180:183], v151 offset:49152
	ds_read_b128 v[184:187], v151 offset:50176
	ds_read_b128 v[188:191], v151 offset:51200
	ds_read_b128 v[194:197], v151 offset:52224
	ds_read_b128 v[198:201], v151 offset:53248
	ds_read_b128 v[202:205], v151 offset:54272
	ds_read_b128 v[206:209], v151 offset:55296
	ds_read_b128 v[210:213], v151 offset:56320
	global_load_lds_dwordx4 v[144:145], off
	s_add_i32 m0, s38, 0x2000
	s_add_u32 s36, s36, 0x100080
	v_lshl_add_u64 v[144:145], v[214:215], 0, s[12:13]
	s_addc_u32 s37, s37, 0
	s_add_i32 s38, s66, s44
	global_load_lds_dwordx4 v[144:145], off
	v_lshl_add_u64 v[144:145], s[36:37], 0, v[130:131]
	s_mov_b32 m0, s38
	s_nop 0
	global_load_lds_dwordx4 v[144:145], off
	v_lshl_add_u64 v[144:145], s[36:37], 0, v[128:129]
	s_add_i32 m0, s38, 0x2000
	s_nop 0
	global_load_lds_dwordx4 v[144:145], off
	v_lshl_add_u64 v[144:145], v[216:217], 0, s[12:13]
	s_mov_b32 m0, s51
	s_nop 0
	global_load_lds_dwordx4 v[144:145], off
	v_lshl_add_u64 v[144:145], v[218:219], 0, s[12:13]
	s_mov_b32 m0, s52
	s_nop 0
	global_load_lds_dwordx4 v[144:145], off
	s_waitcnt vmcnt(8)
	s_waitcnt lgkmcnt(0)
	s_barrier
	s_waitcnt lgkmcnt(0)
	v_mfma_f32_16x16x32_bf16 v[60:63], v[140:143], v[180:183], v[60:63]
	v_mfma_f32_16x16x32_bf16 v[56:59], v[156:159], v[180:183], v[56:59]
	v_mfma_f32_16x16x32_bf16 v[52:55], v[140:143], v[188:191], v[52:55]
	v_mfma_f32_16x16x32_bf16 v[48:51], v[156:159], v[188:191], v[48:51]
	v_mfma_f32_16x16x32_bf16 v[44:47], v[140:143], v[198:201], v[44:47]
	v_mfma_f32_16x16x32_bf16 v[36:39], v[156:159], v[198:201], v[36:39]
	v_mfma_f32_16x16x32_bf16 v[28:31], v[140:143], v[206:209], v[28:31]
	v_mfma_f32_16x16x32_bf16 v[8:11], v[156:159], v[206:209], v[8:11]
	v_mfma_f32_16x16x32_bf16 v[60:63], v[152:155], v[184:187], v[60:63]
	v_mfma_f32_16x16x32_bf16 v[56:59], v[160:163], v[184:187], v[56:59]
	v_mfma_f32_16x16x32_bf16 v[52:55], v[152:155], v[194:197], v[52:55]
	v_mfma_f32_16x16x32_bf16 v[48:51], v[160:163], v[194:197], v[48:51]
	v_mfma_f32_16x16x32_bf16 v[44:47], v[152:155], v[202:205], v[44:47]
	v_mfma_f32_16x16x32_bf16 v[36:39], v[160:163], v[202:205], v[36:39]
	v_mfma_f32_16x16x32_bf16 v[28:31], v[152:155], v[210:213], v[28:31]
	v_mfma_f32_16x16x32_bf16 v[8:11], v[160:163], v[210:213], v[8:11]
	v_mfma_f32_16x16x32_bf16 v[40:43], v[164:167], v[180:183], v[40:43]
	v_mfma_f32_16x16x32_bf16 v[32:35], v[172:175], v[180:183], v[32:35]
	v_mfma_f32_16x16x32_bf16 v[24:27], v[164:167], v[188:191], v[24:27]
	v_mfma_f32_16x16x32_bf16 v[20:23], v[172:175], v[188:191], v[20:23]
	v_mfma_f32_16x16x32_bf16 v[16:19], v[164:167], v[198:201], v[16:19]
	v_mfma_f32_16x16x32_bf16 v[12:15], v[172:175], v[198:201], v[12:15]
	v_mfma_f32_16x16x32_bf16 v[4:7], v[164:167], v[206:209], v[4:7]
	v_mfma_f32_16x16x32_bf16 v[0:3], v[172:175], v[206:209], v[0:3]
	v_mfma_f32_16x16x32_bf16 v[40:43], v[168:171], v[184:187], v[40:43]
	v_mfma_f32_16x16x32_bf16 v[32:35], v[176:179], v[184:187], v[32:35]
	v_mfma_f32_16x16x32_bf16 v[24:27], v[168:171], v[194:197], v[24:27]
	v_mfma_f32_16x16x32_bf16 v[20:23], v[176:179], v[194:197], v[20:23]
	v_mfma_f32_16x16x32_bf16 v[16:19], v[168:171], v[202:205], v[16:19]
	v_mfma_f32_16x16x32_bf16 v[12:15], v[176:179], v[202:205], v[12:15]
	v_mfma_f32_16x16x32_bf16 v[4:7], v[168:171], v[210:213], v[4:7]
	v_mfma_f32_16x16x32_bf16 v[0:3], v[176:179], v[210:213], v[0:3]
	s_barrier
	s_add_i32 s64, s64, 2
	s_add_u32 s26, s26, 0x100
	s_addc_u32 s27, s27, 0
	s_add_u32 s62, s62, 0x100
	s_addc_u32 s63, s63, 0
	s_cmp_gt_u32 s64, 61
	s_cbranch_scc0 .LBB0_1224
	s_and_b64 vcc, exec, s[14:15]
	s_cbranch_vccz .LBB0_1227
	s_barrier
